# v012 + P5 epilogue: the two 8-byte G stores of each row group (n=0,1 passes) merged into one 16-byte store (halves store instructions and L2 partial-sector writes)
# speedup vs baseline: 1.0074x; 1.0066x over previous
;     __device__ __forceinline__ void operator()(f32x4 (&acc)[2][2][4][2], const Unit& u, int wr, int wc, int fr, int fq) const {
;     ...
; #pragma unroll
;         for (int ai = 0; ai < 2; ++ai)
; #pragma unroll
;             for (int m = 0; m < 4; ++m) {
;                 const float rs = __builtin_amdgcn_rsqf(rp[ai * HALF + m * 16] * (1.f / DM) + EPS);
; #pragma unroll
;                 for (int bj = 0; bj < 2; ++bj)
; #pragma unroll
;                     for (int n = 0; n < 2; ++n) acc[ai][bj][m][n] = acc[ai][bj][m][n] * rs;
;             }
; #pragma unroll
;         for (int ai = 0; ai < 2; ++ai)
; #pragma unroll
;             for (int mm = 0; mm < 2; ++mm) {
;                 const int m = mm * 3;
;                 const bool hl = mm == 0 ? (fr < 2) : (fr >= 14);
;                 if (hl) {
;                     const int slot = mm == 0 ? fr : fr - 12;
;                     const int seg = (u.pm * BM + ai * HALF + wr * 64) >> 6;
;                     bf16_t* hp = HALO + (size_t)(seg * 4 + slot) * (2 * DFF) + ch0;
; #pragma unroll
;                     for (int bj = 0; bj < 2; ++bj) *(u32x4*)(hp + bj * DFF) = pack8(acc[ai][bj][m][0], acc[ai][bj][m][1]);
;                 }
;             }
; #pragma unroll
;         for (int n = 0; n < 2; ++n) {
;             const f32x4 g0 = tp[0 * 32 + n], g1 = tp[1 * 32 + n], g2 = tp[2 * 32 + n], gb = tp[3 * 32 + n], v0 = tp[4 * 32 + n], v1 = tp[5 * 32 + n], v2 = tp[6 * 32 + n], vb = tp[7 * 32 + n];
;             bf16_t* gp0 = G + (size_t)(u.pm * BM + wr * 64 + fr) * DFF + ch0 + 4 * n;
; #pragma unroll
;             for (int ai = 0; ai < 2; ++ai)
; #pragma unroll
;                 for (int m = 0; m < 4; ++m) {
;                     f32x4 gp4, gn4, vp4, vn4;
;                     const f32x4 gc4 = acc[ai][0][m][n], vc4 = acc[ai][1][m][n];
; #pragma unroll
;                     for (int j = 0; j < 4; ++j) {
;                         const float gpl = m > 0 ? acc[ai][0][m - 1][n][j] : 0.f, gnf = m < 3 ? acc[ai][0][m + 1][n][j] : 0.f;
;                         const float vpl = m > 0 ? acc[ai][1][m - 1][n][j] : 0.f, vnf = m < 3 ? acc[ai][1][m + 1][n][j] : 0.f;
;                         gp4[j] = dpp_prev(gpl, gc4[j]); gn4[j] = dpp_next(gnf, gc4[j]); vp4[j] = dpp_prev(vpl, vc4[j]); vn4[j] = dpp_next(vnf, vc4[j]);
;                     }
;                     const f32x4 gate = g0 * gp4 + g1 * gc4 + g2 * gn4 + gb;
.LBB0_997:
	s_or_b64 exec, exec, s[70:71]
	s_nop 0
	v_fmamk_f32 v56, v183, 0x3a000000, v215
	v_rsq_f32_e32 v126, v56
	v_add_u32_e32 v131, s0, v212
	v_or_b32_e32 v140, s33, v209
	v_mov_b64_e32 v[96:97], s[36:37]
	v_pk_mul_f32 v[184:185], v[78:79], v[126:127] op_sel_hi:[1,0]
	v_pk_mul_f32 v[188:189], v[76:77], v[126:127] op_sel_hi:[1,0]
	v_pk_mul_f32 v[182:183], v[66:67], v[126:127] op_sel_hi:[1,0]
	v_pk_mul_f32 v[186:187], v[64:65], v[126:127] op_sel_hi:[1,0]
	ds_read_b128 v[84:87], v131
	ds_read_b128 v[80:83], v131 offset:512
	ds_read_b128 v[76:79], v131 offset:1024
	ds_read_b128 v[72:75], v131 offset:1536
	ds_read_b128 v[68:71], v131 offset:2048
	ds_read_b128 v[64:67], v131 offset:2560
	ds_read_b128 v[60:63], v131 offset:3072
	ds_read_b128 v[56:59], v131 offset:3584
	s_movk_i32 s0, 0x2c00
	v_mad_i64_i32 v[96:97], s[14:15], v140, s0, v[96:97]
	v_mov_b32_dpp v193, v141 row_ror:1 row_mask:0xf bank_mask:0xf bound_ctrl:1
	v_lshl_add_u64 v[96:97], v[190:191], 1, v[96:97]
	v_mov_b32_e32 v200, v193
	v_mov_b32_dpp v198, v188 row_ror:15 row_mask:0xf bank_mask:0xf bound_ctrl:1
	v_mov_b32_e32 v194, v193
	v_mov_b32_dpp v190, v186 row_ror:15 row_mask:0xf bank_mask:0xf bound_ctrl:1
	v_mov_b32_e32 v201, v193
	v_mov_b32_dpp v199, v189 row_ror:15 row_mask:0xf bank_mask:0xf bound_ctrl:1
	v_mov_b32_e32 v195, v193
	v_mov_b32_dpp v191, v187 row_ror:15 row_mask:0xf bank_mask:0xf bound_ctrl:1
	v_mov_b32_e32 v204, v193
	v_mov_b32_dpp v202, v184 row_ror:15 row_mask:0xf bank_mask:0xf bound_ctrl:1
	v_mov_b32_e32 v192, v193
	v_mov_b32_dpp v196, v182 row_ror:15 row_mask:0xf bank_mask:0xf bound_ctrl:1
	v_mov_b32_e32 v205, v193
	v_mov_b32_dpp v203, v185 row_ror:15 row_mask:0xf bank_mask:0xf bound_ctrl:1
	v_mov_b32_dpp v197, v183 row_ror:15 row_mask:0xf bank_mask:0xf bound_ctrl:1
	v_mov_b32_dpp v200, v178 row_shr:1 row_mask:0xf bank_mask:0xf
	v_mov_b32_dpp v198, v178 row_shl:1 row_mask:0xf bank_mask:0xf
	v_mov_b32_dpp v194, v180 row_shr:1 row_mask:0xf bank_mask:0xf
	v_mov_b32_dpp v190, v180 row_shl:1 row_mask:0xf bank_mask:0xf
	v_mov_b32_dpp v201, v179 row_shr:1 row_mask:0xf bank_mask:0xf
	v_mov_b32_dpp v199, v179 row_shl:1 row_mask:0xf bank_mask:0xf
	v_mov_b32_dpp v195, v181 row_shr:1 row_mask:0xf bank_mask:0xf
	v_mov_b32_dpp v191, v181 row_shl:1 row_mask:0xf bank_mask:0xf
	v_mov_b32_dpp v204, v156 row_shr:1 row_mask:0xf bank_mask:0xf
	v_mov_b32_dpp v202, v156 row_shl:1 row_mask:0xf bank_mask:0xf
	v_mov_b32_dpp v192, v162 row_shr:1 row_mask:0xf bank_mask:0xf
	v_mov_b32_dpp v196, v162 row_shl:1 row_mask:0xf bank_mask:0xf
	v_mov_b32_dpp v205, v157 row_shr:1 row_mask:0xf bank_mask:0xf
	v_mov_b32_dpp v203, v157 row_shl:1 row_mask:0xf bank_mask:0xf
	v_mov_b32_dpp v193, v163 row_shr:1 row_mask:0xf bank_mask:0xf
	v_mov_b32_dpp v197, v163 row_shl:1 row_mask:0xf bank_mask:0xf
	s_and_saveexec_b64 s[70:71], s[10:11]
	s_cbranch_execz .LBB0_999
	s_waitcnt lgkmcnt(0)
	v_pk_mul_f32 v[200:201], v[84:85], v[200:201]
	v_pk_mul_f32 v[204:205], v[86:87], v[204:205]
	v_pk_fma_f32 v[200:201], v[178:179], v[80:81], v[200:201]
	v_pk_fma_f32 v[204:205], v[156:157], v[82:83], v[204:205]
	v_pk_fma_f32 v[198:199], v[76:77], v[198:199], v[200:201]
	v_pk_fma_f32 v[200:201], v[78:79], v[202:203], v[204:205]
	v_pk_add_f32 v[198:199], v[72:73], v[198:199]
	v_pk_add_f32 v[200:201], v[74:75], v[200:201]
	v_mul_f32_e32 v140, 0xbfb8aa3b, v198
	v_exp_f32_e32 v202, v140
	v_mul_f32_e32 v140, 0xbfb8aa3b, v199
	v_mul_f32_e32 v151, 0xbfb8aa3b, v200
	v_exp_f32_e32 v204, v151
	v_mul_f32_e32 v151, 0xbfb8aa3b, v201
	v_exp_f32_e32 v203, v140
	v_exp_f32_e32 v205, v151
	v_pk_mul_f32 v[194:195], v[68:69], v[194:195]
	v_pk_mul_f32 v[192:193], v[70:71], v[192:193]
	v_pk_add_f32 v[202:203], v[202:203], 1.0 op_sel_hi:[1,0]
	v_pk_add_f32 v[204:205], v[204:205], 1.0 op_sel_hi:[1,0]
	v_rcp_f32_e32 v202, v202
	v_rcp_f32_e32 v203, v203
	v_rcp_f32_e32 v204, v204
	v_rcp_f32_e32 v205, v205
	v_pk_fma_f32 v[194:195], v[180:181], v[64:65], v[194:195]
	v_pk_fma_f32 v[192:193], v[162:163], v[66:67], v[192:193]
	v_pk_fma_f32 v[190:191], v[60:61], v[190:191], v[194:195]
	v_pk_fma_f32 v[192:193], v[62:63], v[196:197], v[192:193]
	v_pk_add_f32 v[190:191], v[56:57], v[190:191]
	v_pk_mul_f32 v[194:195], v[198:199], v[202:203]
	v_pk_add_f32 v[192:193], v[58:59], v[192:193]
	v_pk_mul_f32 v[196:197], v[200:201], v[204:205]
	v_pk_mul_f32 v[190:191], v[190:191], v[194:195]
	v_pk_mul_f32 v[192:193], v[192:193], v[196:197]
	v_cvt_pk_bf16_f32 v190, v190, v191
	s_nop 0
	v_cvt_pk_bf16_f32 v191, v192, v193
	v_mov_b32_e32 v216, v190
	v_mov_b32_e32 v217, v191
;     __device__ __forceinline__ void operator()(f32x4 (&acc)[2][2][4][2], const Unit& u, int wr, int wc, int fr, int fq) const {
;     ...
;             for (int m = 0; m < 4; ++m) {
;                 const float rs = __builtin_amdgcn_rsqf(rp[ai * HALF + m * 16] * (1.f / DM) + EPS);
; #pragma unroll
;                 for (int bj = 0; bj < 2; ++bj)
; #pragma unroll
;                     for (int n = 0; n < 2; ++n) acc[ai][bj][m][n] = acc[ai][bj][m][n] * rs;
;             }
; #pragma unroll
;         for (int ai = 0; ai < 2; ++ai)
; #pragma unroll
;             for (int mm = 0; mm < 2; ++mm) {
;                 const int m = mm * 3;
;                 const bool hl = mm == 0 ? (fr < 2) : (fr >= 14);
;                 if (hl) {
;                     const int slot = mm == 0 ? fr : fr - 12;
;                     const int seg = (u.pm * BM + ai * HALF + wr * 64) >> 6;
;                     bf16_t* hp = HALO + (size_t)(seg * 4 + slot) * (2 * DFF) + ch0;
; #pragma unroll
;                     for (int bj = 0; bj < 2; ++bj) *(u32x4*)(hp + bj * DFF) = pack8(acc[ai][bj][m][0], acc[ai][bj][m][1]);
;                 }
;             }
; #pragma unroll
;         for (int n = 0; n < 2; ++n) {
;             const f32x4 g0 = tp[0 * 32 + n], g1 = tp[1 * 32 + n], g2 = tp[2 * 32 + n], gb = tp[3 * 32 + n], v0 = tp[4 * 32 + n], v1 = tp[5 * 32 + n], v2 = tp[6 * 32 + n], vb = tp[7 * 32 + n];
;             bf16_t* gp0 = G + (size_t)(u.pm * BM + wr * 64 + fr) * DFF + ch0 + 4 * n;
; #pragma unroll
;             for (int ai = 0; ai < 2; ++ai)
; #pragma unroll
;                 for (int m = 0; m < 4; ++m) {
;                     f32x4 gp4, gn4, vp4, vn4;
;                     const f32x4 gc4 = acc[ai][0][m][n], vc4 = acc[ai][1][m][n];
; #pragma unroll
;                     for (int j = 0; j < 4; ++j) {
;                         const float gpl = m > 0 ? acc[ai][0][m - 1][n][j] : 0.f, gnf = m < 3 ? acc[ai][0][m + 1][n][j] : 0.f;
;                         const float vpl = m > 0 ? acc[ai][1][m - 1][n][j] : 0.f, vnf = m < 3 ? acc[ai][1][m + 1][n][j] : 0.f;
;                         gp4[j] = dpp_prev(gpl, gc4[j]); gn4[j] = dpp_next(gnf, gc4[j]); vp4[j] = dpp_prev(vpl, vc4[j]); vn4[j] = dpp_next(vnf, vc4[j]);
;                     }
;                     const f32x4 gate = g0 * gp4 + g1 * gc4 + g2 * gn4 + gb;
;                     const f32x4 val = v0 * vp4 + v1 * vc4 + v2 * vn4 + vb;
.LBB0_999:
	s_or_b64 exec, exec, s[70:71]
	v_fmamk_f32 v140, v150, 0x3a000000, v215
	v_rsq_f32_e32 v150, v140
	s_nop 0
	v_pk_mul_f32 v[54:55], v[54:55], v[150:151] op_sel_hi:[1,0]
	v_pk_mul_f32 v[52:53], v[52:53], v[150:151] op_sel_hi:[1,0]
	v_pk_mul_f32 v[50:51], v[50:51], v[150:151] op_sel_hi:[1,0]
	v_pk_mul_f32 v[48:49], v[48:49], v[150:151] op_sel_hi:[1,0]
	v_mov_b32_dpp v178, v178 row_ror:1 row_mask:0xf bank_mask:0xf bound_ctrl:1
	v_mov_b32_dpp v179, v179 row_ror:1 row_mask:0xf bank_mask:0xf bound_ctrl:1
	v_mov_b32_dpp v156, v156 row_ror:1 row_mask:0xf bank_mask:0xf bound_ctrl:1
	v_mov_b32_dpp v157, v157 row_ror:1 row_mask:0xf bank_mask:0xf bound_ctrl:1
	v_mov_b32_dpp v178, v188 row_shr:1 row_mask:0xf bank_mask:0xf
	v_mov_b32_dpp v179, v189 row_shr:1 row_mask:0xf bank_mask:0xf
	v_mov_b32_dpp v156, v184 row_shr:1 row_mask:0xf bank_mask:0xf
	v_mov_b32_dpp v157, v185 row_shr:1 row_mask:0xf bank_mask:0xf
	v_mov_b32_dpp v190, v52 row_ror:15 row_mask:0xf bank_mask:0xf bound_ctrl:1
	v_mov_b32_dpp v191, v53 row_ror:15 row_mask:0xf bank_mask:0xf bound_ctrl:1
	v_mov_b32_dpp v194, v54 row_ror:15 row_mask:0xf bank_mask:0xf bound_ctrl:1
	v_mov_b32_dpp v195, v55 row_ror:15 row_mask:0xf bank_mask:0xf bound_ctrl:1
	s_waitcnt lgkmcnt(0)
	v_pk_mul_f32 v[178:179], v[84:85], v[178:179]
	v_pk_mul_f32 v[156:157], v[86:87], v[156:157]
	v_mov_b32_dpp v190, v188 row_shl:1 row_mask:0xf bank_mask:0xf
	v_mov_b32_dpp v191, v189 row_shl:1 row_mask:0xf bank_mask:0xf
	v_mov_b32_dpp v194, v184 row_shl:1 row_mask:0xf bank_mask:0xf
	v_mov_b32_dpp v195, v185 row_shl:1 row_mask:0xf bank_mask:0xf
	v_pk_fma_f32 v[156:157], v[184:185], v[82:83], v[156:157]
	v_pk_fma_f32 v[178:179], v[188:189], v[80:81], v[178:179]
	v_pk_fma_f32 v[156:157], v[78:79], v[194:195], v[156:157]
	v_pk_fma_f32 v[178:179], v[76:77], v[190:191], v[178:179]
	v_pk_add_f32 v[156:157], v[74:75], v[156:157]
	v_pk_add_f32 v[178:179], v[72:73], v[178:179]
	v_mul_f32_e32 v151, 0xbfb8aa3b, v156
	v_mul_f32_e32 v140, 0xbfb8aa3b, v178
	v_exp_f32_e32 v190, v140
	v_mul_f32_e32 v140, 0xbfb8aa3b, v179
	v_exp_f32_e32 v194, v151
	v_mul_f32_e32 v151, 0xbfb8aa3b, v157
	v_exp_f32_e32 v195, v151
	v_exp_f32_e32 v191, v140
	v_mov_b32_dpp v180, v180 row_ror:1 row_mask:0xf bank_mask:0xf bound_ctrl:1
	v_mov_b32_dpp v181, v181 row_ror:1 row_mask:0xf bank_mask:0xf bound_ctrl:1
	v_mov_b32_dpp v162, v162 row_ror:1 row_mask:0xf bank_mask:0xf bound_ctrl:1
	v_mov_b32_dpp v163, v163 row_ror:1 row_mask:0xf bank_mask:0xf bound_ctrl:1
	v_pk_add_f32 v[194:195], v[194:195], 1.0 op_sel_hi:[1,0]
	v_pk_add_f32 v[190:191], v[190:191], 1.0 op_sel_hi:[1,0]
	v_mov_b32_dpp v180, v186 row_shr:1 row_mask:0xf bank_mask:0xf
	v_mov_b32_dpp v181, v187 row_shr:1 row_mask:0xf bank_mask:0xf
	v_mov_b32_dpp v162, v182 row_shr:1 row_mask:0xf bank_mask:0xf
	v_mov_b32_dpp v163, v183 row_shr:1 row_mask:0xf bank_mask:0xf
	v_rcp_f32_e32 v190, v190
	v_rcp_f32_e32 v191, v191
	v_rcp_f32_e32 v194, v194
	v_rcp_f32_e32 v195, v195
	v_mov_b32_dpp v192, v48 row_ror:15 row_mask:0xf bank_mask:0xf bound_ctrl:1
	v_mov_b32_dpp v193, v49 row_ror:15 row_mask:0xf bank_mask:0xf bound_ctrl:1
	v_mov_b32_dpp v196, v50 row_ror:15 row_mask:0xf bank_mask:0xf bound_ctrl:1
	v_mov_b32_dpp v197, v51 row_ror:15 row_mask:0xf bank_mask:0xf bound_ctrl:1
	v_pk_mul_f32 v[162:163], v[70:71], v[162:163]
	v_pk_mul_f32 v[180:181], v[68:69], v[180:181]
	v_mov_b32_dpp v192, v186 row_shl:1 row_mask:0xf bank_mask:0xf
	v_mov_b32_dpp v193, v187 row_shl:1 row_mask:0xf bank_mask:0xf
	v_mov_b32_dpp v196, v182 row_shl:1 row_mask:0xf bank_mask:0xf
	v_mov_b32_dpp v197, v183 row_shl:1 row_mask:0xf bank_mask:0xf
	v_pk_fma_f32 v[180:181], v[186:187], v[64:65], v[180:181]
	v_pk_fma_f32 v[162:163], v[182:183], v[66:67], v[162:163]
	v_pk_fma_f32 v[180:181], v[60:61], v[192:193], v[180:181]
	v_pk_fma_f32 v[162:163], v[62:63], v[196:197], v[162:163]
	v_pk_add_f32 v[180:181], v[56:57], v[180:181]
	v_pk_add_f32 v[162:163], v[58:59], v[162:163]
	v_pk_mul_f32 v[178:179], v[178:179], v[190:191]
	v_pk_mul_f32 v[156:157], v[156:157], v[194:195]
	s_nop 0
	v_pk_mul_f32 v[156:157], v[162:163], v[156:157]
	v_pk_mul_f32 v[162:163], v[180:181], v[178:179]
	s_nop 0
	v_cvt_pk_bf16_f32 v162, v162, v163
	v_cvt_pk_bf16_f32 v163, v156, v157
	v_add_co_u32_e32 v156, vcc, s92, v96
	s_nop 1
	v_addc_co_u32_e32 v157, vcc, 0, v97, vcc
	v_mov_b32_e32 v218, v162
	v_mov_b32_e32 v219, v163
	v_mov_b32_dpp v162, v188 row_ror:1 row_mask:0xf bank_mask:0xf bound_ctrl:1
	v_mov_b32_dpp v163, v189 row_ror:1 row_mask:0xf bank_mask:0xf bound_ctrl:1
	v_mov_b32_dpp v178, v176 row_ror:15 row_mask:0xf bank_mask:0xf bound_ctrl:1
	v_mov_b32_dpp v162, v52 row_shr:1 row_mask:0xf bank_mask:0xf
	v_mov_b32_dpp v163, v53 row_shr:1 row_mask:0xf bank_mask:0xf
	v_mov_b32_dpp v179, v177 row_ror:15 row_mask:0xf bank_mask:0xf bound_ctrl:1
	v_mov_b32_dpp v184, v184 row_ror:1 row_mask:0xf bank_mask:0xf bound_ctrl:1
	v_mov_b32_dpp v185, v185 row_ror:1 row_mask:0xf bank_mask:0xf bound_ctrl:1
	v_pk_mul_f32 v[162:163], v[84:85], v[162:163]
	v_mov_b32_dpp v178, v52 row_shl:1 row_mask:0xf bank_mask:0xf
	v_mov_b32_dpp v179, v53 row_shl:1 row_mask:0xf bank_mask:0xf
	v_mov_b32_dpp v184, v54 row_shr:1 row_mask:0xf bank_mask:0xf
	v_mov_b32_dpp v185, v55 row_shr:1 row_mask:0xf bank_mask:0xf
	v_pk_fma_f32 v[162:163], v[52:53], v[80:81], v[162:163]
	v_mov_b32_dpp v188, v174 row_ror:15 row_mask:0xf bank_mask:0xf bound_ctrl:1
	v_mov_b32_dpp v189, v175 row_ror:15 row_mask:0xf bank_mask:0xf bound_ctrl:1
	v_pk_mul_f32 v[184:185], v[86:87], v[184:185]
	v_pk_fma_f32 v[162:163], v[76:77], v[178:179], v[162:163]
	v_mov_b32_dpp v188, v54 row_shl:1 row_mask:0xf bank_mask:0xf
; __device__ __forceinline__ u32x2 pack4(f32x4 a) { u32x2 w; w.x = cvt_pk_bf16(a[0], a[1]); w.y = cvt_pk_bf16(a[2], a[3]); return w; }
;     __device__ __forceinline__ void operator()(f32x4 (&acc)[2][2][4][2], const Unit& u, int wr, int wc, int fr, int fq) const {
;     ...
;         for (int n = 0; n < 2; ++n) {
;             const f32x4 g0 = tp[0 * 32 + n], g1 = tp[1 * 32 + n], g2 = tp[2 * 32 + n], gb = tp[3 * 32 + n], v0 = tp[4 * 32 + n], v1 = tp[5 * 32 + n], v2 = tp[6 * 32 + n], vb = tp[7 * 32 + n];
;             bf16_t* gp0 = G + (size_t)(u.pm * BM + wr * 64 + fr) * DFF + ch0 + 4 * n;
; #pragma unroll
;             for (int ai = 0; ai < 2; ++ai)
; #pragma unroll
;                 for (int m = 0; m < 4; ++m) {
;                     f32x4 gp4, gn4, vp4, vn4;
;                     const f32x4 gc4 = acc[ai][0][m][n], vc4 = acc[ai][1][m][n];
; #pragma unroll
;                     for (int j = 0; j < 4; ++j) {
;                         const float gpl = m > 0 ? acc[ai][0][m - 1][n][j] : 0.f, gnf = m < 3 ? acc[ai][0][m + 1][n][j] : 0.f;
;                         const float vpl = m > 0 ? acc[ai][1][m - 1][n][j] : 0.f, vnf = m < 3 ? acc[ai][1][m + 1][n][j] : 0.f;
;                         gp4[j] = dpp_prev(gpl, gc4[j]); gn4[j] = dpp_next(gnf, gc4[j]); vp4[j] = dpp_prev(vpl, vc4[j]); vn4[j] = dpp_next(vnf, vc4[j]);
;                     }
;                     const f32x4 gate = g0 * gp4 + g1 * gc4 + g2 * gn4 + gb;
;                     const f32x4 val = v0 * vp4 + v1 * vc4 + v2 * vn4 + vb;
;                     const f32x4 ea = gate * (-1.4426950408889634f);
;                     f32x4 den;
; #pragma unroll
;                     for (int j = 0; j < 4; ++j) den[j] = __builtin_amdgcn_exp2f(ea[j]);
;                     den = den + 1.0f;
; #pragma unroll
;                     for (int j = 0; j < 4; ++j) den[j] = __builtin_amdgcn_rcpf(den[j]);
;                     const f32x4 o = gate * den * val;
;                     const bool interior = !((m == 0 && fr == 0) || (m == 3 && fr == 15));
;                     if (interior) *(u32x2*)(gp0 + (size_t)(ai * HALF + m * 16) * DFF) = pack4(o);
	v_mov_b32_dpp v189, v55 row_shl:1 row_mask:0xf bank_mask:0xf
	v_pk_fma_f32 v[184:185], v[54:55], v[82:83], v[184:185]
	v_pk_add_f32 v[162:163], v[72:73], v[162:163]
	v_pk_fma_f32 v[178:179], v[78:79], v[188:189], v[184:185]
	v_mul_f32_e32 v140, 0xbfb8aa3b, v162
	v_pk_add_f32 v[178:179], v[74:75], v[178:179]
	v_exp_f32_e32 v184, v140
	v_mul_f32_e32 v140, 0xbfb8aa3b, v163
	v_mul_f32_e32 v151, 0xbfb8aa3b, v178
	v_exp_f32_e32 v185, v140
	v_exp_f32_e32 v188, v151
	v_mul_f32_e32 v151, 0xbfb8aa3b, v179
	v_exp_f32_e32 v189, v151
	v_mov_b32_dpp v180, v186 row_ror:1 row_mask:0xf bank_mask:0xf bound_ctrl:1
	v_mov_b32_dpp v181, v187 row_ror:1 row_mask:0xf bank_mask:0xf bound_ctrl:1
	v_pk_add_f32 v[184:185], v[184:185], 1.0 op_sel_hi:[1,0]
	v_mov_b32_dpp v180, v48 row_shr:1 row_mask:0xf bank_mask:0xf
	v_mov_b32_dpp v181, v49 row_shr:1 row_mask:0xf bank_mask:0xf
	v_rcp_f32_e32 v184, v184
	v_rcp_f32_e32 v185, v185
	v_mov_b32_dpp v186, v172 row_ror:15 row_mask:0xf bank_mask:0xf bound_ctrl:1
	v_mov_b32_dpp v187, v173 row_ror:15 row_mask:0xf bank_mask:0xf bound_ctrl:1
	v_mov_b32_dpp v182, v182 row_ror:1 row_mask:0xf bank_mask:0xf bound_ctrl:1
	v_mov_b32_dpp v183, v183 row_ror:1 row_mask:0xf bank_mask:0xf bound_ctrl:1
	v_pk_add_f32 v[188:189], v[188:189], 1.0 op_sel_hi:[1,0]
	v_pk_mul_f32 v[180:181], v[68:69], v[180:181]
	v_mov_b32_dpp v186, v48 row_shl:1 row_mask:0xf bank_mask:0xf
	v_mov_b32_dpp v187, v49 row_shl:1 row_mask:0xf bank_mask:0xf
	v_mov_b32_dpp v182, v50 row_shr:1 row_mask:0xf bank_mask:0xf
	v_mov_b32_dpp v183, v51 row_shr:1 row_mask:0xf bank_mask:0xf
	v_rcp_f32_e32 v188, v188
	v_rcp_f32_e32 v189, v189
	v_pk_fma_f32 v[180:181], v[48:49], v[64:65], v[180:181]
	v_mov_b32_dpp v190, v154 row_ror:15 row_mask:0xf bank_mask:0xf bound_ctrl:1
	v_mov_b32_dpp v191, v155 row_ror:15 row_mask:0xf bank_mask:0xf bound_ctrl:1
	v_pk_mul_f32 v[182:183], v[70:71], v[182:183]
	v_pk_fma_f32 v[180:181], v[60:61], v[186:187], v[180:181]
	v_mov_b32_dpp v190, v50 row_shl:1 row_mask:0xf bank_mask:0xf
	v_mov_b32_dpp v191, v51 row_shl:1 row_mask:0xf bank_mask:0xf
	v_pk_fma_f32 v[182:183], v[50:51], v[66:67], v[182:183]
	v_pk_add_f32 v[180:181], v[56:57], v[180:181]
	v_pk_mul_f32 v[162:163], v[162:163], v[184:185]
	v_pk_fma_f32 v[182:183], v[62:63], v[190:191], v[182:183]
	v_pk_mul_f32 v[162:163], v[180:181], v[162:163]
	v_pk_add_f32 v[182:183], v[58:59], v[182:183]
	v_pk_mul_f32 v[178:179], v[178:179], v[188:189]
	v_cvt_pk_bf16_f32 v180, v162, v163
	v_add_co_u32_e32 v162, vcc, s93, v96
	v_pk_mul_f32 v[178:179], v[182:183], v[178:179]
	s_nop 0
	v_addc_co_u32_e32 v163, vcc, 0, v97, vcc
	v_cvt_pk_bf16_f32 v181, v178, v179
	v_mov_b32_e32 v220, v180
	v_mov_b32_e32 v221, v181
	v_mov_b32_dpp v179, v141 row_ror:15 row_mask:0xf bank_mask:0xf bound_ctrl:1
	v_mov_b32_dpp v182, v52 row_ror:1 row_mask:0xf bank_mask:0xf bound_ctrl:1
	v_mov_b32_e32 v180, v179
	v_mov_b32_dpp v52, v48 row_ror:1 row_mask:0xf bank_mask:0xf bound_ctrl:1
	v_mov_b32_e32 v48, v179
	v_mov_b32_dpp v183, v53 row_ror:1 row_mask:0xf bank_mask:0xf bound_ctrl:1
	v_mov_b32_e32 v181, v179
	v_mov_b32_dpp v53, v49 row_ror:1 row_mask:0xf bank_mask:0xf bound_ctrl:1
	v_mov_b32_e32 v49, v179
	v_mov_b32_dpp v184, v54 row_ror:1 row_mask:0xf bank_mask:0xf bound_ctrl:1
	v_mov_b32_e32 v54, v179
	v_mov_b32_dpp v50, v50 row_ror:1 row_mask:0xf bank_mask:0xf bound_ctrl:1
	v_mov_b32_e32 v178, v179
	v_mov_b32_dpp v185, v55 row_ror:1 row_mask:0xf bank_mask:0xf bound_ctrl:1
	v_mov_b32_e32 v55, v179
	v_mov_b32_dpp v51, v51 row_ror:1 row_mask:0xf bank_mask:0xf bound_ctrl:1
	v_mov_b32_dpp v182, v176 row_shr:1 row_mask:0xf bank_mask:0xf
	v_mov_b32_dpp v180, v176 row_shl:1 row_mask:0xf bank_mask:0xf
	v_mov_b32_dpp v52, v172 row_shr:1 row_mask:0xf bank_mask:0xf
	v_mov_b32_dpp v48, v172 row_shl:1 row_mask:0xf bank_mask:0xf
	v_mov_b32_dpp v183, v177 row_shr:1 row_mask:0xf bank_mask:0xf
	v_mov_b32_dpp v181, v177 row_shl:1 row_mask:0xf bank_mask:0xf
	v_mov_b32_dpp v53, v173 row_shr:1 row_mask:0xf bank_mask:0xf
	v_mov_b32_dpp v49, v173 row_shl:1 row_mask:0xf bank_mask:0xf
	v_mov_b32_dpp v184, v174 row_shr:1 row_mask:0xf bank_mask:0xf
	v_mov_b32_dpp v54, v174 row_shl:1 row_mask:0xf bank_mask:0xf
	v_mov_b32_dpp v50, v154 row_shr:1 row_mask:0xf bank_mask:0xf
	v_mov_b32_dpp v178, v154 row_shl:1 row_mask:0xf bank_mask:0xf
	v_mov_b32_dpp v185, v175 row_shr:1 row_mask:0xf bank_mask:0xf
	v_mov_b32_dpp v55, v175 row_shl:1 row_mask:0xf bank_mask:0xf
	v_mov_b32_dpp v51, v155 row_shr:1 row_mask:0xf bank_mask:0xf
	v_mov_b32_dpp v179, v155 row_shl:1 row_mask:0xf bank_mask:0xf
	s_and_saveexec_b64 s[70:71], s[8:9]
	s_cbranch_execz .LBB0_1001
	v_pk_mul_f32 v[184:185], v[86:87], v[184:185]
	v_pk_mul_f32 v[182:183], v[84:85], v[182:183]
	v_pk_fma_f32 v[174:175], v[174:175], v[82:83], v[184:185]
	v_pk_fma_f32 v[176:177], v[176:177], v[80:81], v[182:183]
	v_pk_fma_f32 v[54:55], v[78:79], v[54:55], v[174:175]
	v_pk_fma_f32 v[176:177], v[76:77], v[180:181], v[176:177]
	v_pk_add_f32 v[54:55], v[74:75], v[54:55]
	v_pk_add_f32 v[174:175], v[72:73], v[176:177]
	v_mul_f32_e32 v151, 0xbfb8aa3b, v54
	v_mul_f32_e32 v140, 0xbfb8aa3b, v174
	v_exp_f32_e32 v176, v140
	v_mul_f32_e32 v140, 0xbfb8aa3b, v175
	v_exp_f32_e32 v180, v151
	v_mul_f32_e32 v151, 0xbfb8aa3b, v55
	v_exp_f32_e32 v181, v151
	v_exp_f32_e32 v177, v140
	v_pk_mul_f32 v[50:51], v[70:71], v[50:51]
	v_pk_mul_f32 v[52:53], v[68:69], v[52:53]
	v_pk_add_f32 v[180:181], v[180:181], 1.0 op_sel_hi:[1,0]
	v_pk_add_f32 v[176:177], v[176:177], 1.0 op_sel_hi:[1,0]
	v_rcp_f32_e32 v180, v180
	v_rcp_f32_e32 v176, v176
	v_rcp_f32_e32 v177, v177
	v_rcp_f32_e32 v181, v181
	v_pk_fma_f32 v[50:51], v[154:155], v[66:67], v[50:51]
	v_pk_fma_f32 v[52:53], v[172:173], v[64:65], v[52:53]
	v_pk_fma_f32 v[50:51], v[62:63], v[178:179], v[50:51]
	v_pk_fma_f32 v[48:49], v[60:61], v[48:49], v[52:53]
	v_pk_add_f32 v[50:51], v[58:59], v[50:51]
	v_pk_add_f32 v[48:49], v[56:57], v[48:49]
	v_pk_mul_f32 v[52:53], v[174:175], v[176:177]
	v_pk_mul_f32 v[54:55], v[54:55], v[180:181]
	v_pk_mul_f32 v[48:49], v[48:49], v[52:53]
	v_pk_mul_f32 v[50:51], v[50:51], v[54:55]
	v_cvt_pk_bf16_f32 v48, v48, v49
	s_nop 0
	v_cvt_pk_bf16_f32 v49, v50, v51
	v_add_co_u32_e32 v50, vcc, 0x84000, v96
	s_nop 1
	v_addc_co_u32_e32 v51, vcc, 0, v97, vcc
	v_mov_b32_e32 v222, v48
	v_mov_b32_e32 v223, v49
;     __device__ __forceinline__ void operator()(f32x4 (&acc)[2][2][4][2], const Unit& u, int wr, int wc, int fr, int fq) const {
;     ...
; #pragma unroll
;         for (int ai = 0; ai < 2; ++ai)
; #pragma unroll
;             for (int m = 0; m < 4; ++m) {
;                 const float rs = __builtin_amdgcn_rsqf(rp[ai * HALF + m * 16] * (1.f / DM) + EPS);
; #pragma unroll
;                 for (int bj = 0; bj < 2; ++bj)
; #pragma unroll
;                     for (int n = 0; n < 2; ++n) acc[ai][bj][m][n] = acc[ai][bj][m][n] * rs;
;             }
; #pragma unroll
;         for (int ai = 0; ai < 2; ++ai)
; #pragma unroll
;             for (int mm = 0; mm < 2; ++mm) {
;                 const int m = mm * 3;
;                 const bool hl = mm == 0 ? (fr < 2) : (fr >= 14);
;                 if (hl) {
;                     const int slot = mm == 0 ? fr : fr - 12;
;                     const int seg = (u.pm * BM + ai * HALF + wr * 64) >> 6;
;                     bf16_t* hp = HALO + (size_t)(seg * 4 + slot) * (2 * DFF) + ch0;
; #pragma unroll
;                     for (int bj = 0; bj < 2; ++bj) *(u32x4*)(hp + bj * DFF) = pack8(acc[ai][bj][m][0], acc[ai][bj][m][1]);
;                 }
;             }
; #pragma unroll
;         for (int n = 0; n < 2; ++n) {
;             const f32x4 g0 = tp[0 * 32 + n], g1 = tp[1 * 32 + n], g2 = tp[2 * 32 + n], gb = tp[3 * 32 + n], v0 = tp[4 * 32 + n], v1 = tp[5 * 32 + n], v2 = tp[6 * 32 + n], vb = tp[7 * 32 + n];
;             bf16_t* gp0 = G + (size_t)(u.pm * BM + wr * 64 + fr) * DFF + ch0 + 4 * n;
; #pragma unroll
;             for (int ai = 0; ai < 2; ++ai)
; #pragma unroll
;                 for (int m = 0; m < 4; ++m) {
;                     f32x4 gp4, gn4, vp4, vn4;
;                     const f32x4 gc4 = acc[ai][0][m][n], vc4 = acc[ai][1][m][n];
; #pragma unroll
;                     for (int j = 0; j < 4; ++j) {
;                         const float gpl = m > 0 ? acc[ai][0][m - 1][n][j] : 0.f, gnf = m < 3 ? acc[ai][0][m + 1][n][j] : 0.f;
;                         const float vpl = m > 0 ? acc[ai][1][m - 1][n][j] : 0.f, vnf = m < 3 ? acc[ai][1][m + 1][n][j] : 0.f;
;                         gp4[j] = dpp_prev(gpl, gc4[j]); gn4[j] = dpp_next(gnf, gc4[j]); vp4[j] = dpp_prev(vpl, vc4[j]); vn4[j] = dpp_next(vnf, vc4[j]);
;                     }
;                     const f32x4 gate = g0 * gp4 + g1 * gc4 + g2 * gn4 + gb;
.LBB0_1001:
	s_or_b64 exec, exec, s[70:71]
	v_fmamk_f32 v48, v127, 0x3a000000, v215
	v_rsq_f32_e32 v154, v48
	s_nop 0
	v_pk_mul_f32 v[46:47], v[46:47], v[154:155] op_sel_hi:[1,0]
	v_pk_mul_f32 v[44:45], v[44:45], v[154:155] op_sel_hi:[1,0]
	v_pk_mul_f32 v[42:43], v[42:43], v[154:155] op_sel_hi:[1,0]
	v_pk_mul_f32 v[40:41], v[40:41], v[154:155] op_sel_hi:[1,0]
	v_mov_b32_dpp v51, v141 row_ror:1 row_mask:0xf bank_mask:0xf bound_ctrl:1
	v_mov_b32_e32 v174, v51
	v_mov_b32_dpp v172, v44 row_ror:15 row_mask:0xf bank_mask:0xf bound_ctrl:1
	v_mov_b32_e32 v52, v51
	v_mov_b32_dpp v48, v40 row_ror:15 row_mask:0xf bank_mask:0xf bound_ctrl:1
	v_mov_b32_e32 v175, v51
	v_mov_b32_dpp v173, v45 row_ror:15 row_mask:0xf bank_mask:0xf bound_ctrl:1
	v_mov_b32_e32 v53, v51
	v_mov_b32_dpp v49, v41 row_ror:15 row_mask:0xf bank_mask:0xf bound_ctrl:1
	v_mov_b32_e32 v178, v51
	v_mov_b32_dpp v176, v46 row_ror:15 row_mask:0xf bank_mask:0xf bound_ctrl:1
	v_mov_b32_e32 v50, v51
	v_mov_b32_dpp v54, v42 row_ror:15 row_mask:0xf bank_mask:0xf bound_ctrl:1
	v_mov_b32_e32 v179, v51
	v_mov_b32_dpp v177, v47 row_ror:15 row_mask:0xf bank_mask:0xf bound_ctrl:1
	v_mov_b32_dpp v55, v43 row_ror:15 row_mask:0xf bank_mask:0xf bound_ctrl:1
	v_mov_b32_dpp v174, v168 row_shr:1 row_mask:0xf bank_mask:0xf
	v_mov_b32_dpp v172, v168 row_shl:1 row_mask:0xf bank_mask:0xf
	v_mov_b32_dpp v52, v170 row_shr:1 row_mask:0xf bank_mask:0xf
	v_mov_b32_dpp v48, v170 row_shl:1 row_mask:0xf bank_mask:0xf
	v_mov_b32_dpp v175, v169 row_shr:1 row_mask:0xf bank_mask:0xf
	v_mov_b32_dpp v173, v169 row_shl:1 row_mask:0xf bank_mask:0xf
	v_mov_b32_dpp v53, v171 row_shr:1 row_mask:0xf bank_mask:0xf
	v_mov_b32_dpp v49, v171 row_shl:1 row_mask:0xf bank_mask:0xf
	v_mov_b32_dpp v178, v164 row_shr:1 row_mask:0xf bank_mask:0xf
	v_mov_b32_dpp v176, v164 row_shl:1 row_mask:0xf bank_mask:0xf
	v_mov_b32_dpp v50, v166 row_shr:1 row_mask:0xf bank_mask:0xf
	v_mov_b32_dpp v54, v166 row_shl:1 row_mask:0xf bank_mask:0xf
	v_mov_b32_dpp v179, v165 row_shr:1 row_mask:0xf bank_mask:0xf
	v_mov_b32_dpp v177, v165 row_shl:1 row_mask:0xf bank_mask:0xf
	v_mov_b32_dpp v51, v167 row_shr:1 row_mask:0xf bank_mask:0xf
	v_mov_b32_dpp v55, v167 row_shl:1 row_mask:0xf bank_mask:0xf
	s_and_saveexec_b64 s[70:71], s[10:11]
	s_cbranch_execz .LBB0_1003
	v_pk_mul_f32 v[178:179], v[86:87], v[178:179]
	v_pk_mul_f32 v[174:175], v[84:85], v[174:175]
	v_pk_fma_f32 v[178:179], v[164:165], v[82:83], v[178:179]
	v_pk_fma_f32 v[174:175], v[168:169], v[80:81], v[174:175]
	v_pk_mul_f32 v[50:51], v[70:71], v[50:51]
	v_pk_fma_f32 v[172:173], v[76:77], v[172:173], v[174:175]
	v_pk_fma_f32 v[174:175], v[78:79], v[176:177], v[178:179]
	v_pk_add_f32 v[172:173], v[72:73], v[172:173]
	v_pk_add_f32 v[174:175], v[74:75], v[174:175]
	v_mul_f32_e32 v127, 0xbfb8aa3b, v172
	v_mul_f32_e32 v140, 0xbfb8aa3b, v174
	v_exp_f32_e32 v176, v127
	v_mul_f32_e32 v127, 0xbfb8aa3b, v173
	v_exp_f32_e32 v178, v140
	v_mul_f32_e32 v140, 0xbfb8aa3b, v175
	v_exp_f32_e32 v179, v140
	v_exp_f32_e32 v177, v127
	v_pk_mul_f32 v[52:53], v[68:69], v[52:53]
	v_pk_fma_f32 v[50:51], v[166:167], v[66:67], v[50:51]
	v_pk_add_f32 v[178:179], v[178:179], 1.0 op_sel_hi:[1,0]
	v_pk_add_f32 v[176:177], v[176:177], 1.0 op_sel_hi:[1,0]
	v_rcp_f32_e32 v178, v178
	v_rcp_f32_e32 v176, v176
	v_rcp_f32_e32 v177, v177
	v_rcp_f32_e32 v179, v179
	v_pk_fma_f32 v[52:53], v[170:171], v[64:65], v[52:53]
	v_pk_fma_f32 v[50:51], v[62:63], v[54:55], v[50:51]
	v_pk_fma_f32 v[48:49], v[60:61], v[48:49], v[52:53]
	v_pk_add_f32 v[50:51], v[58:59], v[50:51]
	v_pk_add_f32 v[48:49], v[56:57], v[48:49]
	v_pk_mul_f32 v[52:53], v[172:173], v[176:177]
	v_pk_mul_f32 v[54:55], v[174:175], v[178:179]
	v_pk_mul_f32 v[48:49], v[48:49], v[52:53]
	v_pk_mul_f32 v[50:51], v[50:51], v[54:55]
	v_cvt_pk_bf16_f32 v48, v48, v49
	s_nop 0
	v_cvt_pk_bf16_f32 v49, v50, v51
	v_add_co_u32_e32 v50, vcc, 0x160000, v96
	s_nop 1
	v_addc_co_u32_e32 v51, vcc, 0, v97, vcc
	v_mov_b32_e32 v224, v48
	v_mov_b32_e32 v225, v49
.LBB0_1003:
	s_or_b64 exec, exec, s[70:71]
	v_fmamk_f32 v48, v152, 0x3a000000, v215
	v_rsq_f32_e32 v152, v48
	s_nop 0
	v_pk_mul_f32 v[38:39], v[38:39], v[152:153] op_sel_hi:[1,0]
	v_pk_mul_f32 v[36:37], v[36:37], v[152:153] op_sel_hi:[1,0]
	v_pk_mul_f32 v[34:35], v[34:35], v[152:153] op_sel_hi:[1,0]
	v_pk_mul_f32 v[32:33], v[32:33], v[152:153] op_sel_hi:[1,0]
	v_mov_b32_dpp v48, v168 row_ror:1 row_mask:0xf bank_mask:0xf bound_ctrl:1
	v_mov_b32_dpp v49, v169 row_ror:1 row_mask:0xf bank_mask:0xf bound_ctrl:1
	v_mov_b32_dpp v164, v164 row_ror:1 row_mask:0xf bank_mask:0xf bound_ctrl:1
	v_mov_b32_dpp v48, v44 row_shr:1 row_mask:0xf bank_mask:0xf
	v_mov_b32_dpp v49, v45 row_shr:1 row_mask:0xf bank_mask:0xf
	v_mov_b32_dpp v165, v165 row_ror:1 row_mask:0xf bank_mask:0xf bound_ctrl:1
	v_mov_b32_dpp v50, v36 row_ror:15 row_mask:0xf bank_mask:0xf bound_ctrl:1
	v_mov_b32_dpp v51, v37 row_ror:15 row_mask:0xf bank_mask:0xf bound_ctrl:1
	v_mov_b32_dpp v164, v46 row_shr:1 row_mask:0xf bank_mask:0xf
	v_mov_b32_dpp v165, v47 row_shr:1 row_mask:0xf bank_mask:0xf
	v_pk_mul_f32 v[48:49], v[84:85], v[48:49]
	v_mov_b32_dpp v50, v44 row_shl:1 row_mask:0xf bank_mask:0xf
	v_mov_b32_dpp v51, v45 row_shl:1 row_mask:0xf bank_mask:0xf
	v_mov_b32_dpp v168, v38 row_ror:15 row_mask:0xf bank_mask:0xf bound_ctrl:1
	v_mov_b32_dpp v169, v39 row_ror:15 row_mask:0xf bank_mask:0xf bound_ctrl:1
	v_pk_mul_f32 v[164:165], v[86:87], v[164:165]
	v_pk_fma_f32 v[48:49], v[44:45], v[80:81], v[48:49]
	v_mov_b32_dpp v168, v46 row_shl:1 row_mask:0xf bank_mask:0xf
	v_mov_b32_dpp v169, v47 row_shl:1 row_mask:0xf bank_mask:0xf
	v_pk_fma_f32 v[164:165], v[46:47], v[82:83], v[164:165]
; __device__ __forceinline__ u32x2 pack4(f32x4 a) { u32x2 w; w.x = cvt_pk_bf16(a[0], a[1]); w.y = cvt_pk_bf16(a[2], a[3]); return w; }
;     __device__ __forceinline__ void operator()(f32x4 (&acc)[2][2][4][2], const Unit& u, int wr, int wc, int fr, int fq) const {
;     ...
;         for (int n = 0; n < 2; ++n) {
;             const f32x4 g0 = tp[0 * 32 + n], g1 = tp[1 * 32 + n], g2 = tp[2 * 32 + n], gb = tp[3 * 32 + n], v0 = tp[4 * 32 + n], v1 = tp[5 * 32 + n], v2 = tp[6 * 32 + n], vb = tp[7 * 32 + n];
;             bf16_t* gp0 = G + (size_t)(u.pm * BM + wr * 64 + fr) * DFF + ch0 + 4 * n;
; #pragma unroll
;             for (int ai = 0; ai < 2; ++ai)
; #pragma unroll
;                 for (int m = 0; m < 4; ++m) {
;                     f32x4 gp4, gn4, vp4, vn4;
;                     const f32x4 gc4 = acc[ai][0][m][n], vc4 = acc[ai][1][m][n];
; #pragma unroll
;                     for (int j = 0; j < 4; ++j) {
;                         const float gpl = m > 0 ? acc[ai][0][m - 1][n][j] : 0.f, gnf = m < 3 ? acc[ai][0][m + 1][n][j] : 0.f;
;                         const float vpl = m > 0 ? acc[ai][1][m - 1][n][j] : 0.f, vnf = m < 3 ? acc[ai][1][m + 1][n][j] : 0.f;
;                         gp4[j] = dpp_prev(gpl, gc4[j]); gn4[j] = dpp_next(gnf, gc4[j]); vp4[j] = dpp_prev(vpl, vc4[j]); vn4[j] = dpp_next(vnf, vc4[j]);
;                     }
;                     const f32x4 gate = g0 * gp4 + g1 * gc4 + g2 * gn4 + gb;
;                     const f32x4 val = v0 * vp4 + v1 * vc4 + v2 * vn4 + vb;
;                     const f32x4 ea = gate * (-1.4426950408889634f);
;                     f32x4 den;
; #pragma unroll
;                     for (int j = 0; j < 4; ++j) den[j] = __builtin_amdgcn_exp2f(ea[j]);
;                     den = den + 1.0f;
; #pragma unroll
;                     for (int j = 0; j < 4; ++j) den[j] = __builtin_amdgcn_rcpf(den[j]);
;                     const f32x4 o = gate * den * val;
;                     const bool interior = !((m == 0 && fr == 0) || (m == 3 && fr == 15));
;                     if (interior) *(u32x2*)(gp0 + (size_t)(ai * HALF + m * 16) * DFF) = pack4(o);
	v_pk_fma_f32 v[48:49], v[76:77], v[50:51], v[48:49]
	v_pk_fma_f32 v[50:51], v[78:79], v[168:169], v[164:165]
	v_pk_add_f32 v[48:49], v[72:73], v[48:49]
	v_pk_add_f32 v[50:51], v[74:75], v[50:51]
	v_mul_f32_e32 v127, 0xbfb8aa3b, v48
	v_exp_f32_e32 v164, v127
	v_mul_f32_e32 v127, 0xbfb8aa3b, v49
	v_mul_f32_e32 v140, 0xbfb8aa3b, v50
	v_exp_f32_e32 v168, v140
	v_mul_f32_e32 v140, 0xbfb8aa3b, v51
	v_exp_f32_e32 v165, v127
	v_exp_f32_e32 v169, v140
	v_mov_b32_dpp v52, v170 row_ror:1 row_mask:0xf bank_mask:0xf bound_ctrl:1
	v_mov_b32_dpp v53, v171 row_ror:1 row_mask:0xf bank_mask:0xf bound_ctrl:1
	v_pk_add_f32 v[164:165], v[164:165], 1.0 op_sel_hi:[1,0]
	v_mov_b32_dpp v52, v40 row_shr:1 row_mask:0xf bank_mask:0xf
	v_mov_b32_dpp v53, v41 row_shr:1 row_mask:0xf bank_mask:0xf
	v_mov_b32_dpp v166, v166 row_ror:1 row_mask:0xf bank_mask:0xf bound_ctrl:1
	v_mov_b32_dpp v167, v167 row_ror:1 row_mask:0xf bank_mask:0xf bound_ctrl:1
	v_pk_add_f32 v[168:169], v[168:169], 1.0 op_sel_hi:[1,0]
	v_rcp_f32_e32 v164, v164
	v_rcp_f32_e32 v165, v165
	v_mov_b32_dpp v54, v32 row_ror:15 row_mask:0xf bank_mask:0xf bound_ctrl:1
	v_mov_b32_dpp v55, v33 row_ror:15 row_mask:0xf bank_mask:0xf bound_ctrl:1
	v_mov_b32_dpp v166, v42 row_shr:1 row_mask:0xf bank_mask:0xf
	v_mov_b32_dpp v167, v43 row_shr:1 row_mask:0xf bank_mask:0xf
	v_rcp_f32_e32 v168, v168
	v_rcp_f32_e32 v169, v169
	v_pk_mul_f32 v[52:53], v[68:69], v[52:53]
	v_mov_b32_dpp v54, v40 row_shl:1 row_mask:0xf bank_mask:0xf
	v_mov_b32_dpp v55, v41 row_shl:1 row_mask:0xf bank_mask:0xf
	v_mov_b32_dpp v170, v34 row_ror:15 row_mask:0xf bank_mask:0xf bound_ctrl:1
	v_mov_b32_dpp v171, v35 row_ror:15 row_mask:0xf bank_mask:0xf bound_ctrl:1
	v_pk_mul_f32 v[166:167], v[70:71], v[166:167]
	v_pk_fma_f32 v[52:53], v[40:41], v[64:65], v[52:53]
	v_mov_b32_dpp v170, v42 row_shl:1 row_mask:0xf bank_mask:0xf
	v_mov_b32_dpp v171, v43 row_shl:1 row_mask:0xf bank_mask:0xf
	v_pk_fma_f32 v[166:167], v[42:43], v[66:67], v[166:167]
	v_pk_fma_f32 v[52:53], v[60:61], v[54:55], v[52:53]
	v_pk_fma_f32 v[166:167], v[62:63], v[170:171], v[166:167]
	v_pk_add_f32 v[52:53], v[56:57], v[52:53]
	v_pk_mul_f32 v[48:49], v[48:49], v[164:165]
	v_add_co_u32_e32 v164, vcc, s94, v96
	v_pk_add_f32 v[54:55], v[58:59], v[166:167]
	v_pk_mul_f32 v[50:51], v[50:51], v[168:169]
	v_pk_mul_f32 v[48:49], v[52:53], v[48:49]
	v_addc_co_u32_e32 v165, vcc, 0, v97, vcc
	v_pk_mul_f32 v[50:51], v[54:55], v[50:51]
	v_cvt_pk_bf16_f32 v48, v48, v49
	s_nop 0
	v_cvt_pk_bf16_f32 v49, v50, v51
	v_mov_b32_e32 v226, v48
	v_mov_b32_e32 v227, v49
	v_mov_b32_dpp v44, v44 row_ror:1 row_mask:0xf bank_mask:0xf bound_ctrl:1
	v_mov_b32_dpp v45, v45 row_ror:1 row_mask:0xf bank_mask:0xf bound_ctrl:1
	v_mov_b32_dpp v46, v46 row_ror:1 row_mask:0xf bank_mask:0xf bound_ctrl:1
	v_mov_b32_dpp v47, v47 row_ror:1 row_mask:0xf bank_mask:0xf bound_ctrl:1
	v_mov_b32_dpp v44, v36 row_shr:1 row_mask:0xf bank_mask:0xf
	v_mov_b32_dpp v45, v37 row_shr:1 row_mask:0xf bank_mask:0xf
	v_mov_b32_dpp v46, v38 row_shr:1 row_mask:0xf bank_mask:0xf
	v_mov_b32_dpp v47, v39 row_shr:1 row_mask:0xf bank_mask:0xf
	v_mov_b32_dpp v48, v160 row_ror:15 row_mask:0xf bank_mask:0xf bound_ctrl:1
	v_mov_b32_dpp v49, v161 row_ror:15 row_mask:0xf bank_mask:0xf bound_ctrl:1
	v_mov_b32_dpp v52, v158 row_ror:15 row_mask:0xf bank_mask:0xf bound_ctrl:1
	v_mov_b32_dpp v53, v159 row_ror:15 row_mask:0xf bank_mask:0xf bound_ctrl:1
	v_pk_mul_f32 v[44:45], v[84:85], v[44:45]
	v_pk_mul_f32 v[46:47], v[86:87], v[46:47]
	v_mov_b32_dpp v48, v36 row_shl:1 row_mask:0xf bank_mask:0xf
	v_mov_b32_dpp v49, v37 row_shl:1 row_mask:0xf bank_mask:0xf
	v_mov_b32_dpp v52, v38 row_shl:1 row_mask:0xf bank_mask:0xf
	v_mov_b32_dpp v53, v39 row_shl:1 row_mask:0xf bank_mask:0xf
	v_pk_fma_f32 v[46:47], v[38:39], v[82:83], v[46:47]
	v_pk_fma_f32 v[44:45], v[36:37], v[80:81], v[44:45]
	v_pk_fma_f32 v[46:47], v[78:79], v[52:53], v[46:47]
	v_pk_fma_f32 v[44:45], v[76:77], v[48:49], v[44:45]
	v_pk_add_f32 v[46:47], v[74:75], v[46:47]
	v_pk_add_f32 v[44:45], v[72:73], v[44:45]
	v_mul_f32_e32 v52, 0xbfb8aa3b, v46
	v_mul_f32_e32 v48, 0xbfb8aa3b, v44
	v_mul_f32_e32 v49, 0xbfb8aa3b, v45
	v_mul_f32_e32 v53, 0xbfb8aa3b, v47
	v_exp_f32_e32 v48, v48
	v_exp_f32_e32 v52, v52
	v_exp_f32_e32 v53, v53
	v_exp_f32_e32 v49, v49
	v_mov_b32_dpp v40, v40 row_ror:1 row_mask:0xf bank_mask:0xf bound_ctrl:1
	v_mov_b32_dpp v41, v41 row_ror:1 row_mask:0xf bank_mask:0xf bound_ctrl:1
	v_mov_b32_dpp v42, v42 row_ror:1 row_mask:0xf bank_mask:0xf bound_ctrl:1
	v_mov_b32_dpp v43, v43 row_ror:1 row_mask:0xf bank_mask:0xf bound_ctrl:1
	v_pk_add_f32 v[52:53], v[52:53], 1.0 op_sel_hi:[1,0]
	v_pk_add_f32 v[48:49], v[48:49], 1.0 op_sel_hi:[1,0]
	v_mov_b32_dpp v40, v32 row_shr:1 row_mask:0xf bank_mask:0xf
	v_mov_b32_dpp v41, v33 row_shr:1 row_mask:0xf bank_mask:0xf
	v_mov_b32_dpp v42, v34 row_shr:1 row_mask:0xf bank_mask:0xf
	v_mov_b32_dpp v43, v35 row_shr:1 row_mask:0xf bank_mask:0xf
	v_rcp_f32_e32 v48, v48
	v_rcp_f32_e32 v49, v49
	v_rcp_f32_e32 v52, v52
	v_rcp_f32_e32 v53, v53
	v_mov_b32_dpp v50, v124 row_ror:15 row_mask:0xf bank_mask:0xf bound_ctrl:1
	v_mov_b32_dpp v51, v125 row_ror:15 row_mask:0xf bank_mask:0xf bound_ctrl:1
	v_mov_b32_dpp v54, v118 row_ror:15 row_mask:0xf bank_mask:0xf bound_ctrl:1
	v_mov_b32_dpp v55, v119 row_ror:15 row_mask:0xf bank_mask:0xf bound_ctrl:1
	v_pk_mul_f32 v[42:43], v[70:71], v[42:43]
	v_pk_mul_f32 v[40:41], v[68:69], v[40:41]
	v_mov_b32_dpp v50, v32 row_shl:1 row_mask:0xf bank_mask:0xf
	v_mov_b32_dpp v51, v33 row_shl:1 row_mask:0xf bank_mask:0xf
	v_mov_b32_dpp v54, v34 row_shl:1 row_mask:0xf bank_mask:0xf
	v_mov_b32_dpp v55, v35 row_shl:1 row_mask:0xf bank_mask:0xf
; __device__ __forceinline__ u32x2 pack4(f32x4 a) { u32x2 w; w.x = cvt_pk_bf16(a[0], a[1]); w.y = cvt_pk_bf16(a[2], a[3]); return w; }
;     __device__ __forceinline__ void operator()(f32x4 (&acc)[2][2][4][2], const Unit& u, int wr, int wc, int fr, int fq) const {
;     ...
;         for (int n = 0; n < 2; ++n) {
;             const f32x4 g0 = tp[0 * 32 + n], g1 = tp[1 * 32 + n], g2 = tp[2 * 32 + n], gb = tp[3 * 32 + n], v0 = tp[4 * 32 + n], v1 = tp[5 * 32 + n], v2 = tp[6 * 32 + n], vb = tp[7 * 32 + n];
;             bf16_t* gp0 = G + (size_t)(u.pm * BM + wr * 64 + fr) * DFF + ch0 + 4 * n;
; #pragma unroll
;             for (int ai = 0; ai < 2; ++ai)
; #pragma unroll
;                 for (int m = 0; m < 4; ++m) {
;                     f32x4 gp4, gn4, vp4, vn4;
;                     const f32x4 gc4 = acc[ai][0][m][n], vc4 = acc[ai][1][m][n];
; #pragma unroll
;                     for (int j = 0; j < 4; ++j) {
;                         const float gpl = m > 0 ? acc[ai][0][m - 1][n][j] : 0.f, gnf = m < 3 ? acc[ai][0][m + 1][n][j] : 0.f;
;                         const float vpl = m > 0 ? acc[ai][1][m - 1][n][j] : 0.f, vnf = m < 3 ? acc[ai][1][m + 1][n][j] : 0.f;
;                         gp4[j] = dpp_prev(gpl, gc4[j]); gn4[j] = dpp_next(gnf, gc4[j]); vp4[j] = dpp_prev(vpl, vc4[j]); vn4[j] = dpp_next(vnf, vc4[j]);
;                     }
;                     const f32x4 gate = g0 * gp4 + g1 * gc4 + g2 * gn4 + gb;
;                     const f32x4 val = v0 * vp4 + v1 * vc4 + v2 * vn4 + vb;
;                     const f32x4 ea = gate * (-1.4426950408889634f);
;                     f32x4 den;
; #pragma unroll
;                     for (int j = 0; j < 4; ++j) den[j] = __builtin_amdgcn_exp2f(ea[j]);
;                     den = den + 1.0f;
; #pragma unroll
;                     for (int j = 0; j < 4; ++j) den[j] = __builtin_amdgcn_rcpf(den[j]);
;                     const f32x4 o = gate * den * val;
;                     const bool interior = !((m == 0 && fr == 0) || (m == 3 && fr == 15));
;                     if (interior) *(u32x2*)(gp0 + (size_t)(ai * HALF + m * 16) * DFF) = pack4(o);
	v_pk_fma_f32 v[40:41], v[32:33], v[64:65], v[40:41]
	v_pk_fma_f32 v[42:43], v[34:35], v[66:67], v[42:43]
	v_pk_fma_f32 v[40:41], v[60:61], v[50:51], v[40:41]
	v_pk_fma_f32 v[42:43], v[62:63], v[54:55], v[42:43]
	v_pk_add_f32 v[40:41], v[56:57], v[40:41]
	v_pk_add_f32 v[42:43], v[58:59], v[42:43]
	v_pk_mul_f32 v[44:45], v[44:45], v[48:49]
	v_pk_mul_f32 v[46:47], v[46:47], v[52:53]
	v_add_co_u32_e32 v166, vcc, s95, v96
	v_pk_mul_f32 v[42:43], v[42:43], v[46:47]
	v_pk_mul_f32 v[40:41], v[40:41], v[44:45]
	v_addc_co_u32_e32 v167, vcc, 0, v97, vcc
	v_cvt_pk_bf16_f32 v40, v40, v41
	v_cvt_pk_bf16_f32 v41, v42, v43
	v_mov_b32_e32 v228, v40
	v_mov_b32_e32 v229, v41
	s_nop 0
	v_mov_b32_dpp v41, v141 row_ror:15 row_mask:0xf bank_mask:0xf bound_ctrl:1
	v_mov_b32_dpp v44, v36 row_ror:1 row_mask:0xf bank_mask:0xf bound_ctrl:1
	v_mov_b32_e32 v42, v41
	v_mov_b32_dpp v36, v32 row_ror:1 row_mask:0xf bank_mask:0xf bound_ctrl:1
	v_mov_b32_e32 v32, v41
	v_mov_b32_dpp v45, v37 row_ror:1 row_mask:0xf bank_mask:0xf bound_ctrl:1
	v_mov_b32_e32 v43, v41
	v_mov_b32_dpp v37, v33 row_ror:1 row_mask:0xf bank_mask:0xf bound_ctrl:1
	v_mov_b32_e32 v33, v41
	v_mov_b32_dpp v46, v38 row_ror:1 row_mask:0xf bank_mask:0xf bound_ctrl:1
	v_mov_b32_e32 v38, v41
	v_mov_b32_dpp v34, v34 row_ror:1 row_mask:0xf bank_mask:0xf bound_ctrl:1
	v_mov_b32_e32 v40, v41
	v_mov_b32_dpp v47, v39 row_ror:1 row_mask:0xf bank_mask:0xf bound_ctrl:1
	v_mov_b32_e32 v39, v41
	v_mov_b32_dpp v35, v35 row_ror:1 row_mask:0xf bank_mask:0xf bound_ctrl:1
	v_mov_b32_dpp v44, v160 row_shr:1 row_mask:0xf bank_mask:0xf
	v_mov_b32_dpp v42, v160 row_shl:1 row_mask:0xf bank_mask:0xf
	v_mov_b32_dpp v36, v124 row_shr:1 row_mask:0xf bank_mask:0xf
	v_mov_b32_dpp v32, v124 row_shl:1 row_mask:0xf bank_mask:0xf
	v_mov_b32_dpp v45, v161 row_shr:1 row_mask:0xf bank_mask:0xf
	v_mov_b32_dpp v43, v161 row_shl:1 row_mask:0xf bank_mask:0xf
	v_mov_b32_dpp v37, v125 row_shr:1 row_mask:0xf bank_mask:0xf
	v_mov_b32_dpp v33, v125 row_shl:1 row_mask:0xf bank_mask:0xf
	v_mov_b32_dpp v46, v158 row_shr:1 row_mask:0xf bank_mask:0xf
	v_mov_b32_dpp v38, v158 row_shl:1 row_mask:0xf bank_mask:0xf
	v_mov_b32_dpp v34, v118 row_shr:1 row_mask:0xf bank_mask:0xf
	v_mov_b32_dpp v40, v118 row_shl:1 row_mask:0xf bank_mask:0xf
	v_mov_b32_dpp v47, v159 row_shr:1 row_mask:0xf bank_mask:0xf
	v_mov_b32_dpp v39, v159 row_shl:1 row_mask:0xf bank_mask:0xf
	v_mov_b32_dpp v35, v119 row_shr:1 row_mask:0xf bank_mask:0xf
	v_mov_b32_dpp v41, v119 row_shl:1 row_mask:0xf bank_mask:0xf
	s_and_saveexec_b64 s[70:71], s[8:9]
	s_cbranch_execz .LBB0_1005
	v_pk_mul_f32 v[46:47], v[86:87], v[46:47]
	v_pk_mul_f32 v[44:45], v[84:85], v[44:45]
	v_pk_fma_f32 v[46:47], v[158:159], v[82:83], v[46:47]
	v_pk_fma_f32 v[44:45], v[160:161], v[80:81], v[44:45]
	v_pk_fma_f32 v[38:39], v[78:79], v[38:39], v[46:47]
	v_pk_fma_f32 v[42:43], v[76:77], v[42:43], v[44:45]
	v_pk_add_f32 v[38:39], v[74:75], v[38:39]
	v_pk_add_f32 v[42:43], v[72:73], v[42:43]
	v_mul_f32_e32 v46, 0xbfb8aa3b, v38
	v_mul_f32_e32 v44, 0xbfb8aa3b, v42
	v_mul_f32_e32 v45, 0xbfb8aa3b, v43
	v_mul_f32_e32 v47, 0xbfb8aa3b, v39
	v_exp_f32_e32 v44, v44
	v_exp_f32_e32 v46, v46
	v_exp_f32_e32 v47, v47
	v_exp_f32_e32 v45, v45
	v_pk_mul_f32 v[34:35], v[70:71], v[34:35]
	v_pk_mul_f32 v[36:37], v[68:69], v[36:37]
	v_pk_add_f32 v[46:47], v[46:47], 1.0 op_sel_hi:[1,0]
	v_pk_add_f32 v[44:45], v[44:45], 1.0 op_sel_hi:[1,0]
	v_rcp_f32_e32 v46, v46
	v_rcp_f32_e32 v44, v44
	v_rcp_f32_e32 v45, v45
	v_rcp_f32_e32 v47, v47
	v_pk_fma_f32 v[34:35], v[118:119], v[66:67], v[34:35]
	v_pk_fma_f32 v[36:37], v[124:125], v[64:65], v[36:37]
	v_pk_fma_f32 v[34:35], v[62:63], v[40:41], v[34:35]
	v_pk_fma_f32 v[32:33], v[60:61], v[32:33], v[36:37]
	v_pk_add_f32 v[34:35], v[58:59], v[34:35]
	v_pk_add_f32 v[32:33], v[56:57], v[32:33]
	v_pk_mul_f32 v[36:37], v[42:43], v[44:45]
	v_pk_mul_f32 v[38:39], v[38:39], v[46:47]
	v_pk_mul_f32 v[32:33], v[32:33], v[36:37]
	v_pk_mul_f32 v[34:35], v[34:35], v[38:39]
	v_cvt_pk_bf16_f32 v32, v32, v33
	s_nop 0
	v_cvt_pk_bf16_f32 v33, v34, v35
	v_add_co_u32_e32 v34, vcc, 0x1e4000, v96
	s_nop 1
	v_addc_co_u32_e32 v35, vcc, 0, v97, vcc
	v_mov_b32_e32 v230, v32
	v_mov_b32_e32 v231, v33
.LBB0_1005:
	s_or_b64 exec, exec, s[70:71]
	v_mov_b32_e32 v127, v126
	v_mov_b32_e32 v32, v126
	v_mov_b32_e32 v33, v126
	v_pk_mul_f32 v[58:59], v[30:31], v[32:33]
	v_pk_mul_f32 v[62:63], v[28:29], v[126:127]
	v_pk_mul_f32 v[56:57], v[26:27], v[32:33]
	v_pk_mul_f32 v[60:61], v[24:25], v[126:127]
	ds_read_b128 v[44:47], v131 offset:16
	ds_read_b128 v[40:43], v131 offset:528
	ds_read_b128 v[36:39], v131 offset:1040
	ds_read_b128 v[32:35], v131 offset:1552
	ds_read_b128 v[52:55], v131 offset:2064
	ds_read_b128 v[48:51], v131 offset:2576
	ds_read_b128 v[28:31], v131 offset:3088
	ds_read_b128 v[24:27], v131 offset:3600
	v_mov_b32_dpp v67, v141 row_ror:1 row_mask:0xf bank_mask:0xf bound_ctrl:1
	v_mov_b32_e32 v74, v67
	v_mov_b32_dpp v72, v62 row_ror:15 row_mask:0xf bank_mask:0xf bound_ctrl:1
	v_mov_b32_e32 v68, v67
	v_mov_b32_dpp v64, v60 row_ror:15 row_mask:0xf bank_mask:0xf bound_ctrl:1
	v_mov_b32_e32 v75, v67
	v_mov_b32_dpp v73, v63 row_ror:15 row_mask:0xf bank_mask:0xf bound_ctrl:1
	v_mov_b32_e32 v69, v67
	v_mov_b32_dpp v65, v61 row_ror:15 row_mask:0xf bank_mask:0xf bound_ctrl:1
	v_mov_b32_e32 v78, v67
	v_mov_b32_dpp v76, v58 row_ror:15 row_mask:0xf bank_mask:0xf bound_ctrl:1
	v_mov_b32_e32 v66, v67
	v_mov_b32_dpp v70, v56 row_ror:15 row_mask:0xf bank_mask:0xf bound_ctrl:1
	v_mov_b32_e32 v79, v67
	v_mov_b32_dpp v77, v59 row_ror:15 row_mask:0xf bank_mask:0xf bound_ctrl:1
	v_mov_b32_dpp v71, v57 row_ror:15 row_mask:0xf bank_mask:0xf bound_ctrl:1
	v_mov_b32_dpp v74, v120 row_shr:1 row_mask:0xf bank_mask:0xf
	v_mov_b32_dpp v72, v120 row_shl:1 row_mask:0xf bank_mask:0xf
	v_mov_b32_dpp v68, v116 row_shr:1 row_mask:0xf bank_mask:0xf
	v_mov_b32_dpp v64, v116 row_shl:1 row_mask:0xf bank_mask:0xf
	v_mov_b32_dpp v75, v121 row_shr:1 row_mask:0xf bank_mask:0xf
	v_mov_b32_dpp v73, v121 row_shl:1 row_mask:0xf bank_mask:0xf
	v_mov_b32_dpp v69, v117 row_shr:1 row_mask:0xf bank_mask:0xf
	v_mov_b32_dpp v65, v117 row_shl:1 row_mask:0xf bank_mask:0xf
	v_mov_b32_dpp v78, v122 row_shr:1 row_mask:0xf bank_mask:0xf
	v_mov_b32_dpp v76, v122 row_shl:1 row_mask:0xf bank_mask:0xf
	v_mov_b32_dpp v66, v114 row_shr:1 row_mask:0xf bank_mask:0xf
	v_mov_b32_dpp v70, v114 row_shl:1 row_mask:0xf bank_mask:0xf
	v_mov_b32_dpp v79, v123 row_shr:1 row_mask:0xf bank_mask:0xf
	v_mov_b32_dpp v77, v123 row_shl:1 row_mask:0xf bank_mask:0xf
	v_mov_b32_dpp v67, v115 row_shr:1 row_mask:0xf bank_mask:0xf
	v_mov_b32_dpp v71, v115 row_shl:1 row_mask:0xf bank_mask:0xf
	s_and_saveexec_b64 s[70:71], s[10:11]
	s_cbranch_execz .LBB0_1007
; __device__ __forceinline__ u32x2 pack4(f32x4 a) { u32x2 w; w.x = cvt_pk_bf16(a[0], a[1]); w.y = cvt_pk_bf16(a[2], a[3]); return w; }
;     __device__ __forceinline__ void operator()(f32x4 (&acc)[2][2][4][2], const Unit& u, int wr, int wc, int fr, int fq) const {
;     ...
;         for (int n = 0; n < 2; ++n) {
;             const f32x4 g0 = tp[0 * 32 + n], g1 = tp[1 * 32 + n], g2 = tp[2 * 32 + n], gb = tp[3 * 32 + n], v0 = tp[4 * 32 + n], v1 = tp[5 * 32 + n], v2 = tp[6 * 32 + n], vb = tp[7 * 32 + n];
;             bf16_t* gp0 = G + (size_t)(u.pm * BM + wr * 64 + fr) * DFF + ch0 + 4 * n;
; #pragma unroll
;             for (int ai = 0; ai < 2; ++ai)
; #pragma unroll
;                 for (int m = 0; m < 4; ++m) {
;                     f32x4 gp4, gn4, vp4, vn4;
;                     const f32x4 gc4 = acc[ai][0][m][n], vc4 = acc[ai][1][m][n];
; #pragma unroll
;                     for (int j = 0; j < 4; ++j) {
;                         const float gpl = m > 0 ? acc[ai][0][m - 1][n][j] : 0.f, gnf = m < 3 ? acc[ai][0][m + 1][n][j] : 0.f;
;                         const float vpl = m > 0 ? acc[ai][1][m - 1][n][j] : 0.f, vnf = m < 3 ? acc[ai][1][m + 1][n][j] : 0.f;
;                         gp4[j] = dpp_prev(gpl, gc4[j]); gn4[j] = dpp_next(gnf, gc4[j]); vp4[j] = dpp_prev(vpl, vc4[j]); vn4[j] = dpp_next(vnf, vc4[j]);
;                     }
;                     const f32x4 gate = g0 * gp4 + g1 * gc4 + g2 * gn4 + gb;
;                     const f32x4 val = v0 * vp4 + v1 * vc4 + v2 * vn4 + vb;
;                     const f32x4 ea = gate * (-1.4426950408889634f);
;                     f32x4 den;
; #pragma unroll
;                     for (int j = 0; j < 4; ++j) den[j] = __builtin_amdgcn_exp2f(ea[j]);
;                     den = den + 1.0f;
; #pragma unroll
;                     for (int j = 0; j < 4; ++j) den[j] = __builtin_amdgcn_rcpf(den[j]);
;                     const f32x4 o = gate * den * val;
;                     const bool interior = !((m == 0 && fr == 0) || (m == 3 && fr == 15));
;                     if (interior) *(u32x2*)(gp0 + (size_t)(ai * HALF + m * 16) * DFF) = pack4(o);
	s_waitcnt lgkmcnt(0)
	v_pk_mul_f32 v[74:75], v[44:45], v[74:75]
	v_pk_mul_f32 v[78:79], v[46:47], v[78:79]
	v_pk_fma_f32 v[74:75], v[120:121], v[40:41], v[74:75]
	v_pk_fma_f32 v[78:79], v[122:123], v[42:43], v[78:79]
	v_pk_fma_f32 v[72:73], v[36:37], v[72:73], v[74:75]
	v_pk_fma_f32 v[74:75], v[38:39], v[76:77], v[78:79]
	v_pk_add_f32 v[72:73], v[32:33], v[72:73]
	v_pk_add_f32 v[74:75], v[34:35], v[74:75]
	v_mul_f32_e32 v76, 0xbfb8aa3b, v72
	v_mul_f32_e32 v77, 0xbfb8aa3b, v73
	v_exp_f32_e32 v76, v76
	v_mul_f32_e32 v78, 0xbfb8aa3b, v74
	v_mul_f32_e32 v79, 0xbfb8aa3b, v75
	v_exp_f32_e32 v77, v77
	v_exp_f32_e32 v78, v78
	v_exp_f32_e32 v79, v79
	v_pk_mul_f32 v[68:69], v[52:53], v[68:69]
	v_pk_add_f32 v[76:77], v[76:77], 1.0 op_sel_hi:[1,0]
	v_pk_mul_f32 v[66:67], v[54:55], v[66:67]
	v_pk_add_f32 v[78:79], v[78:79], 1.0 op_sel_hi:[1,0]
	v_rcp_f32_e32 v76, v76
	v_rcp_f32_e32 v77, v77
	v_rcp_f32_e32 v78, v78
	v_rcp_f32_e32 v79, v79
	v_pk_fma_f32 v[68:69], v[116:117], v[48:49], v[68:69]
	v_pk_fma_f32 v[66:67], v[114:115], v[50:51], v[66:67]
	v_pk_fma_f32 v[64:65], v[28:29], v[64:65], v[68:69]
	v_pk_fma_f32 v[66:67], v[30:31], v[70:71], v[66:67]
	v_pk_add_f32 v[64:65], v[24:25], v[64:65]
	v_pk_mul_f32 v[68:69], v[72:73], v[76:77]
	v_pk_add_f32 v[66:67], v[26:27], v[66:67]
	v_pk_mul_f32 v[70:71], v[74:75], v[78:79]
	v_pk_mul_f32 v[64:65], v[64:65], v[68:69]
	v_pk_mul_f32 v[66:67], v[66:67], v[70:71]
	v_cvt_pk_bf16_f32 v64, v64, v65
	s_nop 0
	v_cvt_pk_bf16_f32 v65, v66, v67
	v_mov_b32_e32 v232, v216
	v_mov_b32_e32 v233, v217
	v_mov_b32_e32 v234, v64
	v_mov_b32_e32 v235, v65
	global_store_dwordx4 v[96:97], v[232:235], off
.LBB0_1007:
	s_or_b64 exec, exec, s[70:71]
	v_mov_b32_e32 v151, v150
	v_mov_b32_e32 v64, v150
	v_mov_b32_e32 v65, v150
	v_pk_mul_f32 v[22:23], v[22:23], v[64:65]
	v_pk_mul_f32 v[20:21], v[20:21], v[150:151]
	v_pk_mul_f32 v[18:19], v[18:19], v[64:65]
	v_pk_mul_f32 v[16:17], v[16:17], v[150:151]
	v_mov_b32_dpp v64, v120 row_ror:1 row_mask:0xf bank_mask:0xf bound_ctrl:1
	v_mov_b32_dpp v65, v121 row_ror:1 row_mask:0xf bank_mask:0xf bound_ctrl:1
	v_mov_b32_dpp v72, v122 row_ror:1 row_mask:0xf bank_mask:0xf bound_ctrl:1
	v_mov_b32_dpp v64, v62 row_shr:1 row_mask:0xf bank_mask:0xf
	v_mov_b32_dpp v65, v63 row_shr:1 row_mask:0xf bank_mask:0xf
	v_mov_b32_dpp v73, v123 row_ror:1 row_mask:0xf bank_mask:0xf bound_ctrl:1
	v_mov_b32_dpp v66, v20 row_ror:15 row_mask:0xf bank_mask:0xf bound_ctrl:1
	v_mov_b32_dpp v67, v21 row_ror:15 row_mask:0xf bank_mask:0xf bound_ctrl:1
	v_mov_b32_dpp v72, v58 row_shr:1 row_mask:0xf bank_mask:0xf
	v_mov_b32_dpp v73, v59 row_shr:1 row_mask:0xf bank_mask:0xf
	s_waitcnt lgkmcnt(0)
	v_pk_mul_f32 v[64:65], v[44:45], v[64:65]
	v_mov_b32_dpp v66, v62 row_shl:1 row_mask:0xf bank_mask:0xf
	v_mov_b32_dpp v67, v63 row_shl:1 row_mask:0xf bank_mask:0xf
	v_mov_b32_dpp v74, v22 row_ror:15 row_mask:0xf bank_mask:0xf bound_ctrl:1
	v_mov_b32_dpp v75, v23 row_ror:15 row_mask:0xf bank_mask:0xf bound_ctrl:1
	v_pk_mul_f32 v[72:73], v[46:47], v[72:73]
	v_pk_fma_f32 v[64:65], v[62:63], v[40:41], v[64:65]
	v_mov_b32_dpp v74, v58 row_shl:1 row_mask:0xf bank_mask:0xf
	v_mov_b32_dpp v75, v59 row_shl:1 row_mask:0xf bank_mask:0xf
	v_pk_fma_f32 v[72:73], v[58:59], v[42:43], v[72:73]
	v_pk_fma_f32 v[64:65], v[36:37], v[66:67], v[64:65]
	v_pk_fma_f32 v[66:67], v[38:39], v[74:75], v[72:73]
	v_pk_add_f32 v[64:65], v[32:33], v[64:65]
	v_pk_add_f32 v[66:67], v[34:35], v[66:67]
	v_mul_f32_e32 v72, 0xbfb8aa3b, v64
	v_mul_f32_e32 v73, 0xbfb8aa3b, v65
	v_exp_f32_e32 v72, v72
	v_mul_f32_e32 v74, 0xbfb8aa3b, v66
	v_mul_f32_e32 v75, 0xbfb8aa3b, v67
	v_exp_f32_e32 v73, v73
	v_exp_f32_e32 v74, v74
	v_exp_f32_e32 v75, v75
	v_mov_b32_dpp v68, v116 row_ror:1 row_mask:0xf bank_mask:0xf bound_ctrl:1
	v_mov_b32_dpp v69, v117 row_ror:1 row_mask:0xf bank_mask:0xf bound_ctrl:1
	v_pk_add_f32 v[72:73], v[72:73], 1.0 op_sel_hi:[1,0]
	v_mov_b32_dpp v68, v60 row_shr:1 row_mask:0xf bank_mask:0xf
	v_mov_b32_dpp v69, v61 row_shr:1 row_mask:0xf bank_mask:0xf
	v_mov_b32_dpp v76, v114 row_ror:1 row_mask:0xf bank_mask:0xf bound_ctrl:1
	v_mov_b32_dpp v77, v115 row_ror:1 row_mask:0xf bank_mask:0xf bound_ctrl:1
	v_pk_add_f32 v[74:75], v[74:75], 1.0 op_sel_hi:[1,0]
	v_rcp_f32_e32 v72, v72
	v_rcp_f32_e32 v73, v73
	v_mov_b32_dpp v70, v16 row_ror:15 row_mask:0xf bank_mask:0xf bound_ctrl:1
	v_mov_b32_dpp v71, v17 row_ror:15 row_mask:0xf bank_mask:0xf bound_ctrl:1
	v_mov_b32_dpp v76, v56 row_shr:1 row_mask:0xf bank_mask:0xf
	v_mov_b32_dpp v77, v57 row_shr:1 row_mask:0xf bank_mask:0xf
	v_rcp_f32_e32 v74, v74
	v_rcp_f32_e32 v75, v75
	v_pk_mul_f32 v[68:69], v[52:53], v[68:69]
	v_mov_b32_dpp v70, v60 row_shl:1 row_mask:0xf bank_mask:0xf
	v_mov_b32_dpp v71, v61 row_shl:1 row_mask:0xf bank_mask:0xf
	v_mov_b32_dpp v78, v18 row_ror:15 row_mask:0xf bank_mask:0xf bound_ctrl:1
	v_mov_b32_dpp v79, v19 row_ror:15 row_mask:0xf bank_mask:0xf bound_ctrl:1
	v_pk_mul_f32 v[76:77], v[54:55], v[76:77]
	v_pk_fma_f32 v[68:69], v[60:61], v[48:49], v[68:69]
	v_mov_b32_dpp v78, v56 row_shl:1 row_mask:0xf bank_mask:0xf
	v_mov_b32_dpp v79, v57 row_shl:1 row_mask:0xf bank_mask:0xf
	v_pk_fma_f32 v[76:77], v[56:57], v[50:51], v[76:77]
	v_pk_fma_f32 v[68:69], v[28:29], v[70:71], v[68:69]
	v_pk_fma_f32 v[76:77], v[30:31], v[78:79], v[76:77]
	v_pk_add_f32 v[68:69], v[24:25], v[68:69]
	v_pk_mul_f32 v[64:65], v[64:65], v[72:73]
	v_pk_add_f32 v[70:71], v[26:27], v[76:77]
	v_pk_mul_f32 v[66:67], v[66:67], v[74:75]
	v_pk_mul_f32 v[64:65], v[68:69], v[64:65]
	v_pk_mul_f32 v[66:67], v[70:71], v[66:67]
	v_cvt_pk_bf16_f32 v64, v64, v65
	s_nop 0
	v_cvt_pk_bf16_f32 v65, v66, v67
	v_mov_b32_e32 v232, v218
	v_mov_b32_e32 v233, v219
; __device__ __forceinline__ u32x2 pack4(f32x4 a) { u32x2 w; w.x = cvt_pk_bf16(a[0], a[1]); w.y = cvt_pk_bf16(a[2], a[3]); return w; }
;     __device__ __forceinline__ void operator()(f32x4 (&acc)[2][2][4][2], const Unit& u, int wr, int wc, int fr, int fq) const {
;     ...
;         for (int n = 0; n < 2; ++n) {
;             const f32x4 g0 = tp[0 * 32 + n], g1 = tp[1 * 32 + n], g2 = tp[2 * 32 + n], gb = tp[3 * 32 + n], v0 = tp[4 * 32 + n], v1 = tp[5 * 32 + n], v2 = tp[6 * 32 + n], vb = tp[7 * 32 + n];
;             bf16_t* gp0 = G + (size_t)(u.pm * BM + wr * 64 + fr) * DFF + ch0 + 4 * n;
; #pragma unroll
;             for (int ai = 0; ai < 2; ++ai)
; #pragma unroll
;                 for (int m = 0; m < 4; ++m) {
;                     f32x4 gp4, gn4, vp4, vn4;
;                     const f32x4 gc4 = acc[ai][0][m][n], vc4 = acc[ai][1][m][n];
; #pragma unroll
;                     for (int j = 0; j < 4; ++j) {
;                         const float gpl = m > 0 ? acc[ai][0][m - 1][n][j] : 0.f, gnf = m < 3 ? acc[ai][0][m + 1][n][j] : 0.f;
;                         const float vpl = m > 0 ? acc[ai][1][m - 1][n][j] : 0.f, vnf = m < 3 ? acc[ai][1][m + 1][n][j] : 0.f;
;                         gp4[j] = dpp_prev(gpl, gc4[j]); gn4[j] = dpp_next(gnf, gc4[j]); vp4[j] = dpp_prev(vpl, vc4[j]); vn4[j] = dpp_next(vnf, vc4[j]);
;                     }
;                     const f32x4 gate = g0 * gp4 + g1 * gc4 + g2 * gn4 + gb;
;                     const f32x4 val = v0 * vp4 + v1 * vc4 + v2 * vn4 + vb;
;                     const f32x4 ea = gate * (-1.4426950408889634f);
;                     f32x4 den;
; #pragma unroll
;                     for (int j = 0; j < 4; ++j) den[j] = __builtin_amdgcn_exp2f(ea[j]);
;                     den = den + 1.0f;
; #pragma unroll
;                     for (int j = 0; j < 4; ++j) den[j] = __builtin_amdgcn_rcpf(den[j]);
;                     const f32x4 o = gate * den * val;
;                     const bool interior = !((m == 0 && fr == 0) || (m == 3 && fr == 15));
;                     if (interior) *(u32x2*)(gp0 + (size_t)(ai * HALF + m * 16) * DFF) = pack4(o);
	v_mov_b32_e32 v234, v64
	v_mov_b32_e32 v235, v65
	global_store_dwordx4 v[156:157], v[232:235], off
	v_mov_b32_dpp v62, v62 row_ror:1 row_mask:0xf bank_mask:0xf bound_ctrl:1
	v_mov_b32_dpp v63, v63 row_ror:1 row_mask:0xf bank_mask:0xf bound_ctrl:1
	v_mov_b32_dpp v58, v58 row_ror:1 row_mask:0xf bank_mask:0xf bound_ctrl:1
	v_mov_b32_dpp v59, v59 row_ror:1 row_mask:0xf bank_mask:0xf bound_ctrl:1
	v_mov_b32_dpp v62, v20 row_shr:1 row_mask:0xf bank_mask:0xf
	v_mov_b32_dpp v63, v21 row_shr:1 row_mask:0xf bank_mask:0xf
	v_mov_b32_dpp v58, v22 row_shr:1 row_mask:0xf bank_mask:0xf
	v_mov_b32_dpp v59, v23 row_shr:1 row_mask:0xf bank_mask:0xf
	v_mov_b32_dpp v64, v112 row_ror:15 row_mask:0xf bank_mask:0xf bound_ctrl:1
	v_mov_b32_dpp v65, v113 row_ror:15 row_mask:0xf bank_mask:0xf bound_ctrl:1
	v_mov_b32_dpp v68, v110 row_ror:15 row_mask:0xf bank_mask:0xf bound_ctrl:1
	v_mov_b32_dpp v69, v111 row_ror:15 row_mask:0xf bank_mask:0xf bound_ctrl:1
	v_pk_mul_f32 v[62:63], v[44:45], v[62:63]
	v_pk_mul_f32 v[58:59], v[46:47], v[58:59]
	v_mov_b32_dpp v64, v20 row_shl:1 row_mask:0xf bank_mask:0xf
	v_mov_b32_dpp v65, v21 row_shl:1 row_mask:0xf bank_mask:0xf
	v_mov_b32_dpp v68, v22 row_shl:1 row_mask:0xf bank_mask:0xf
	v_mov_b32_dpp v69, v23 row_shl:1 row_mask:0xf bank_mask:0xf
	v_pk_fma_f32 v[58:59], v[22:23], v[42:43], v[58:59]
	v_pk_fma_f32 v[62:63], v[20:21], v[40:41], v[62:63]
	v_pk_fma_f32 v[58:59], v[38:39], v[68:69], v[58:59]
	v_pk_fma_f32 v[62:63], v[36:37], v[64:65], v[62:63]
	v_pk_add_f32 v[58:59], v[34:35], v[58:59]
	v_pk_add_f32 v[62:63], v[32:33], v[62:63]
	v_mul_f32_e32 v68, 0xbfb8aa3b, v58
	v_mul_f32_e32 v64, 0xbfb8aa3b, v62
	v_mul_f32_e32 v65, 0xbfb8aa3b, v63
	v_mul_f32_e32 v69, 0xbfb8aa3b, v59
	v_exp_f32_e32 v64, v64
	v_exp_f32_e32 v68, v68
	v_exp_f32_e32 v69, v69
	v_exp_f32_e32 v65, v65
	v_mov_b32_dpp v60, v60 row_ror:1 row_mask:0xf bank_mask:0xf bound_ctrl:1
	v_mov_b32_dpp v61, v61 row_ror:1 row_mask:0xf bank_mask:0xf bound_ctrl:1
	v_mov_b32_dpp v56, v56 row_ror:1 row_mask:0xf bank_mask:0xf bound_ctrl:1
	v_mov_b32_dpp v57, v57 row_ror:1 row_mask:0xf bank_mask:0xf bound_ctrl:1
	v_pk_add_f32 v[68:69], v[68:69], 1.0 op_sel_hi:[1,0]
	v_pk_add_f32 v[64:65], v[64:65], 1.0 op_sel_hi:[1,0]
	v_mov_b32_dpp v60, v16 row_shr:1 row_mask:0xf bank_mask:0xf
	v_mov_b32_dpp v61, v17 row_shr:1 row_mask:0xf bank_mask:0xf
	v_mov_b32_dpp v56, v18 row_shr:1 row_mask:0xf bank_mask:0xf
	v_mov_b32_dpp v57, v19 row_shr:1 row_mask:0xf bank_mask:0xf
	v_rcp_f32_e32 v64, v64
	v_rcp_f32_e32 v65, v65
	v_rcp_f32_e32 v68, v68
	v_rcp_f32_e32 v69, v69
	v_mov_b32_dpp v66, v108 row_ror:15 row_mask:0xf bank_mask:0xf bound_ctrl:1
	v_mov_b32_dpp v67, v109 row_ror:15 row_mask:0xf bank_mask:0xf bound_ctrl:1
	v_mov_b32_dpp v70, v106 row_ror:15 row_mask:0xf bank_mask:0xf bound_ctrl:1
	v_mov_b32_dpp v71, v107 row_ror:15 row_mask:0xf bank_mask:0xf bound_ctrl:1
	v_pk_mul_f32 v[56:57], v[54:55], v[56:57]
	v_pk_mul_f32 v[60:61], v[52:53], v[60:61]
	v_mov_b32_dpp v66, v16 row_shl:1 row_mask:0xf bank_mask:0xf
	v_mov_b32_dpp v67, v17 row_shl:1 row_mask:0xf bank_mask:0xf
	v_mov_b32_dpp v70, v18 row_shl:1 row_mask:0xf bank_mask:0xf
	v_mov_b32_dpp v71, v19 row_shl:1 row_mask:0xf bank_mask:0xf
	v_pk_fma_f32 v[60:61], v[16:17], v[48:49], v[60:61]
	v_pk_fma_f32 v[56:57], v[18:19], v[50:51], v[56:57]
	v_pk_fma_f32 v[60:61], v[28:29], v[66:67], v[60:61]
	v_pk_fma_f32 v[56:57], v[30:31], v[70:71], v[56:57]
	v_pk_add_f32 v[60:61], v[24:25], v[60:61]
	v_pk_add_f32 v[56:57], v[26:27], v[56:57]
	v_pk_mul_f32 v[62:63], v[62:63], v[64:65]
	v_pk_mul_f32 v[58:59], v[58:59], v[68:69]
	s_nop 0
	v_pk_mul_f32 v[56:57], v[56:57], v[58:59]
	v_pk_mul_f32 v[58:59], v[60:61], v[62:63]
	s_nop 0
	v_cvt_pk_bf16_f32 v58, v58, v59
	v_cvt_pk_bf16_f32 v59, v56, v57
	v_mov_b32_e32 v232, v220
	v_mov_b32_e32 v233, v221
	v_mov_b32_e32 v234, v58
	v_mov_b32_e32 v235, v59
	global_store_dwordx4 v[162:163], v[232:235], off
	v_mov_b32_dpp v57, v141 row_ror:15 row_mask:0xf bank_mask:0xf bound_ctrl:1
	v_mov_b32_dpp v60, v20 row_ror:1 row_mask:0xf bank_mask:0xf bound_ctrl:1
	v_mov_b32_e32 v58, v57
	v_mov_b32_dpp v20, v16 row_ror:1 row_mask:0xf bank_mask:0xf bound_ctrl:1
	v_mov_b32_e32 v16, v57
	v_mov_b32_dpp v61, v21 row_ror:1 row_mask:0xf bank_mask:0xf bound_ctrl:1
	v_mov_b32_e32 v59, v57
	v_mov_b32_dpp v21, v17 row_ror:1 row_mask:0xf bank_mask:0xf bound_ctrl:1
	v_mov_b32_e32 v17, v57
	v_mov_b32_dpp v62, v22 row_ror:1 row_mask:0xf bank_mask:0xf bound_ctrl:1
	v_mov_b32_e32 v22, v57
	v_mov_b32_dpp v18, v18 row_ror:1 row_mask:0xf bank_mask:0xf bound_ctrl:1
	v_mov_b32_e32 v56, v57
	v_mov_b32_dpp v63, v23 row_ror:1 row_mask:0xf bank_mask:0xf bound_ctrl:1
	v_mov_b32_e32 v23, v57
	v_mov_b32_dpp v19, v19 row_ror:1 row_mask:0xf bank_mask:0xf bound_ctrl:1
	v_mov_b32_dpp v60, v112 row_shr:1 row_mask:0xf bank_mask:0xf
	v_mov_b32_dpp v58, v112 row_shl:1 row_mask:0xf bank_mask:0xf
	v_mov_b32_dpp v20, v108 row_shr:1 row_mask:0xf bank_mask:0xf
	v_mov_b32_dpp v16, v108 row_shl:1 row_mask:0xf bank_mask:0xf
	v_mov_b32_dpp v61, v113 row_shr:1 row_mask:0xf bank_mask:0xf
	v_mov_b32_dpp v59, v113 row_shl:1 row_mask:0xf bank_mask:0xf
	v_mov_b32_dpp v21, v109 row_shr:1 row_mask:0xf bank_mask:0xf
	v_mov_b32_dpp v17, v109 row_shl:1 row_mask:0xf bank_mask:0xf
	v_mov_b32_dpp v62, v110 row_shr:1 row_mask:0xf bank_mask:0xf
	v_mov_b32_dpp v22, v110 row_shl:1 row_mask:0xf bank_mask:0xf
	v_mov_b32_dpp v18, v106 row_shr:1 row_mask:0xf bank_mask:0xf
	v_mov_b32_dpp v56, v106 row_shl:1 row_mask:0xf bank_mask:0xf
	v_mov_b32_dpp v63, v111 row_shr:1 row_mask:0xf bank_mask:0xf
	v_mov_b32_dpp v23, v111 row_shl:1 row_mask:0xf bank_mask:0xf
	v_mov_b32_dpp v19, v107 row_shr:1 row_mask:0xf bank_mask:0xf
	v_mov_b32_dpp v57, v107 row_shl:1 row_mask:0xf bank_mask:0xf
	s_and_saveexec_b64 s[70:71], s[8:9]
	s_cbranch_execz .LBB0_1009
; __device__ __forceinline__ u32x2 pack4(f32x4 a) { u32x2 w; w.x = cvt_pk_bf16(a[0], a[1]); w.y = cvt_pk_bf16(a[2], a[3]); return w; }
;     __device__ __forceinline__ void operator()(f32x4 (&acc)[2][2][4][2], const Unit& u, int wr, int wc, int fr, int fq) const {
;     ...
;         for (int n = 0; n < 2; ++n) {
;             const f32x4 g0 = tp[0 * 32 + n], g1 = tp[1 * 32 + n], g2 = tp[2 * 32 + n], gb = tp[3 * 32 + n], v0 = tp[4 * 32 + n], v1 = tp[5 * 32 + n], v2 = tp[6 * 32 + n], vb = tp[7 * 32 + n];
;             bf16_t* gp0 = G + (size_t)(u.pm * BM + wr * 64 + fr) * DFF + ch0 + 4 * n;
; #pragma unroll
;             for (int ai = 0; ai < 2; ++ai)
; #pragma unroll
;                 for (int m = 0; m < 4; ++m) {
;                     f32x4 gp4, gn4, vp4, vn4;
;                     const f32x4 gc4 = acc[ai][0][m][n], vc4 = acc[ai][1][m][n];
; #pragma unroll
;                     for (int j = 0; j < 4; ++j) {
;                         const float gpl = m > 0 ? acc[ai][0][m - 1][n][j] : 0.f, gnf = m < 3 ? acc[ai][0][m + 1][n][j] : 0.f;
;                         const float vpl = m > 0 ? acc[ai][1][m - 1][n][j] : 0.f, vnf = m < 3 ? acc[ai][1][m + 1][n][j] : 0.f;
;                         gp4[j] = dpp_prev(gpl, gc4[j]); gn4[j] = dpp_next(gnf, gc4[j]); vp4[j] = dpp_prev(vpl, vc4[j]); vn4[j] = dpp_next(vnf, vc4[j]);
;                     }
;                     const f32x4 gate = g0 * gp4 + g1 * gc4 + g2 * gn4 + gb;
;                     const f32x4 val = v0 * vp4 + v1 * vc4 + v2 * vn4 + vb;
;                     const f32x4 ea = gate * (-1.4426950408889634f);
;                     f32x4 den;
; #pragma unroll
;                     for (int j = 0; j < 4; ++j) den[j] = __builtin_amdgcn_exp2f(ea[j]);
;                     den = den + 1.0f;
; #pragma unroll
;                     for (int j = 0; j < 4; ++j) den[j] = __builtin_amdgcn_rcpf(den[j]);
;                     const f32x4 o = gate * den * val;
;                     const bool interior = !((m == 0 && fr == 0) || (m == 3 && fr == 15));
;                     if (interior) *(u32x2*)(gp0 + (size_t)(ai * HALF + m * 16) * DFF) = pack4(o);
	v_pk_mul_f32 v[62:63], v[46:47], v[62:63]
	v_pk_mul_f32 v[60:61], v[44:45], v[60:61]
	v_pk_fma_f32 v[62:63], v[110:111], v[42:43], v[62:63]
	v_pk_fma_f32 v[60:61], v[112:113], v[40:41], v[60:61]
	v_pk_fma_f32 v[22:23], v[38:39], v[22:23], v[62:63]
	v_pk_fma_f32 v[58:59], v[36:37], v[58:59], v[60:61]
	v_pk_add_f32 v[22:23], v[34:35], v[22:23]
	v_pk_add_f32 v[58:59], v[32:33], v[58:59]
	v_mul_f32_e32 v62, 0xbfb8aa3b, v22
	v_mul_f32_e32 v60, 0xbfb8aa3b, v58
	v_mul_f32_e32 v61, 0xbfb8aa3b, v59
	v_mul_f32_e32 v63, 0xbfb8aa3b, v23
	v_exp_f32_e32 v60, v60
	v_exp_f32_e32 v62, v62
	v_exp_f32_e32 v63, v63
	v_exp_f32_e32 v61, v61
	v_pk_mul_f32 v[18:19], v[54:55], v[18:19]
	v_pk_mul_f32 v[20:21], v[52:53], v[20:21]
	v_pk_add_f32 v[62:63], v[62:63], 1.0 op_sel_hi:[1,0]
	v_pk_add_f32 v[60:61], v[60:61], 1.0 op_sel_hi:[1,0]
	v_rcp_f32_e32 v62, v62
	v_rcp_f32_e32 v60, v60
	v_rcp_f32_e32 v61, v61
	v_rcp_f32_e32 v63, v63
	v_pk_fma_f32 v[18:19], v[106:107], v[50:51], v[18:19]
	v_pk_fma_f32 v[20:21], v[108:109], v[48:49], v[20:21]
	v_pk_fma_f32 v[18:19], v[30:31], v[56:57], v[18:19]
	v_pk_fma_f32 v[16:17], v[28:29], v[16:17], v[20:21]
	v_pk_add_f32 v[18:19], v[26:27], v[18:19]
	v_pk_add_f32 v[16:17], v[24:25], v[16:17]
	v_pk_mul_f32 v[20:21], v[58:59], v[60:61]
	v_pk_mul_f32 v[22:23], v[22:23], v[62:63]
	v_pk_mul_f32 v[16:17], v[16:17], v[20:21]
	v_pk_mul_f32 v[18:19], v[18:19], v[22:23]
	v_cvt_pk_bf16_f32 v16, v16, v17
	s_nop 0
	v_cvt_pk_bf16_f32 v17, v18, v19
	v_add_co_u32_e32 v18, vcc, 0x84000, v96
	s_nop 1
	v_addc_co_u32_e32 v19, vcc, 0, v97, vcc
	v_mov_b32_e32 v232, v222
	v_mov_b32_e32 v233, v223
	v_mov_b32_e32 v234, v16
	v_mov_b32_e32 v235, v17
	global_store_dwordx4 v[18:19], v[232:235], off
.LBB0_1009:
	s_or_b64 exec, exec, s[70:71]
	v_mov_b32_e32 v155, v154
	v_mov_b32_e32 v16, v154
	v_mov_b32_e32 v17, v154
	v_pk_mul_f32 v[14:15], v[14:15], v[16:17]
	v_pk_mul_f32 v[12:13], v[12:13], v[154:155]
	v_pk_mul_f32 v[10:11], v[10:11], v[16:17]
	v_pk_mul_f32 v[8:9], v[8:9], v[154:155]
	v_mov_b32_dpp v19, v141 row_ror:1 row_mask:0xf bank_mask:0xf bound_ctrl:1
	v_mov_b32_e32 v58, v19
	v_mov_b32_dpp v56, v12 row_ror:15 row_mask:0xf bank_mask:0xf bound_ctrl:1
	v_mov_b32_e32 v20, v19
	v_mov_b32_dpp v16, v8 row_ror:15 row_mask:0xf bank_mask:0xf bound_ctrl:1
	v_mov_b32_e32 v59, v19
	v_mov_b32_dpp v57, v13 row_ror:15 row_mask:0xf bank_mask:0xf bound_ctrl:1
	v_mov_b32_e32 v21, v19
	v_mov_b32_dpp v17, v9 row_ror:15 row_mask:0xf bank_mask:0xf bound_ctrl:1
	v_mov_b32_e32 v62, v19
	v_mov_b32_dpp v60, v14 row_ror:15 row_mask:0xf bank_mask:0xf bound_ctrl:1
	v_mov_b32_e32 v18, v19
	v_mov_b32_dpp v22, v10 row_ror:15 row_mask:0xf bank_mask:0xf bound_ctrl:1
	v_mov_b32_e32 v63, v19
	v_mov_b32_dpp v61, v15 row_ror:15 row_mask:0xf bank_mask:0xf bound_ctrl:1
	v_mov_b32_dpp v23, v11 row_ror:15 row_mask:0xf bank_mask:0xf bound_ctrl:1
	v_mov_b32_dpp v58, v102 row_shr:1 row_mask:0xf bank_mask:0xf
	v_mov_b32_dpp v56, v102 row_shl:1 row_mask:0xf bank_mask:0xf
	v_mov_b32_dpp v20, v104 row_shr:1 row_mask:0xf bank_mask:0xf
	v_mov_b32_dpp v16, v104 row_shl:1 row_mask:0xf bank_mask:0xf
	v_mov_b32_dpp v59, v103 row_shr:1 row_mask:0xf bank_mask:0xf
	v_mov_b32_dpp v57, v103 row_shl:1 row_mask:0xf bank_mask:0xf
	v_mov_b32_dpp v21, v105 row_shr:1 row_mask:0xf bank_mask:0xf
	v_mov_b32_dpp v17, v105 row_shl:1 row_mask:0xf bank_mask:0xf
	v_mov_b32_dpp v62, v98 row_shr:1 row_mask:0xf bank_mask:0xf
	v_mov_b32_dpp v60, v98 row_shl:1 row_mask:0xf bank_mask:0xf
	v_mov_b32_dpp v18, v100 row_shr:1 row_mask:0xf bank_mask:0xf
	v_mov_b32_dpp v22, v100 row_shl:1 row_mask:0xf bank_mask:0xf
	v_mov_b32_dpp v63, v99 row_shr:1 row_mask:0xf bank_mask:0xf
	v_mov_b32_dpp v61, v99 row_shl:1 row_mask:0xf bank_mask:0xf
	v_mov_b32_dpp v19, v101 row_shr:1 row_mask:0xf bank_mask:0xf
	v_mov_b32_dpp v23, v101 row_shl:1 row_mask:0xf bank_mask:0xf
	s_and_saveexec_b64 s[70:71], s[10:11]
	s_cbranch_execz .LBB0_1011
	v_pk_mul_f32 v[62:63], v[46:47], v[62:63]
	v_pk_mul_f32 v[58:59], v[44:45], v[58:59]
	v_pk_fma_f32 v[62:63], v[98:99], v[42:43], v[62:63]
	v_pk_fma_f32 v[58:59], v[102:103], v[40:41], v[58:59]
	v_pk_mul_f32 v[18:19], v[54:55], v[18:19]
	v_pk_fma_f32 v[56:57], v[36:37], v[56:57], v[58:59]
	v_pk_fma_f32 v[58:59], v[38:39], v[60:61], v[62:63]
	v_pk_add_f32 v[56:57], v[32:33], v[56:57]
	v_pk_add_f32 v[58:59], v[34:35], v[58:59]
	v_mul_f32_e32 v60, 0xbfb8aa3b, v56
	v_mul_f32_e32 v61, 0xbfb8aa3b, v57
	v_mul_f32_e32 v62, 0xbfb8aa3b, v58
	v_mul_f32_e32 v63, 0xbfb8aa3b, v59
	v_exp_f32_e32 v60, v60
	v_exp_f32_e32 v62, v62
	v_exp_f32_e32 v63, v63
	v_exp_f32_e32 v61, v61
	v_pk_mul_f32 v[20:21], v[52:53], v[20:21]
	v_pk_fma_f32 v[18:19], v[100:101], v[50:51], v[18:19]
	v_pk_add_f32 v[62:63], v[62:63], 1.0 op_sel_hi:[1,0]
	v_pk_add_f32 v[60:61], v[60:61], 1.0 op_sel_hi:[1,0]
	v_rcp_f32_e32 v62, v62
	v_rcp_f32_e32 v60, v60
	v_rcp_f32_e32 v61, v61
	v_rcp_f32_e32 v63, v63
	v_pk_fma_f32 v[20:21], v[104:105], v[48:49], v[20:21]
	v_pk_fma_f32 v[18:19], v[30:31], v[22:23], v[18:19]
	v_pk_fma_f32 v[16:17], v[28:29], v[16:17], v[20:21]
	v_pk_add_f32 v[18:19], v[26:27], v[18:19]
	v_pk_add_f32 v[16:17], v[24:25], v[16:17]
	v_pk_mul_f32 v[20:21], v[56:57], v[60:61]
	v_pk_mul_f32 v[22:23], v[58:59], v[62:63]
	v_pk_mul_f32 v[16:17], v[16:17], v[20:21]
	v_pk_mul_f32 v[18:19], v[18:19], v[22:23]
	v_cvt_pk_bf16_f32 v16, v16, v17
	s_nop 0
	v_cvt_pk_bf16_f32 v17, v18, v19
	v_add_co_u32_e32 v18, vcc, 0x160000, v96
	s_nop 1
	v_addc_co_u32_e32 v19, vcc, 0, v97, vcc
	v_mov_b32_e32 v232, v224
	v_mov_b32_e32 v233, v225
	v_mov_b32_e32 v234, v16
	v_mov_b32_e32 v235, v17
	global_store_dwordx4 v[18:19], v[232:235], off
; __device__ __forceinline__ u32x2 pack4(f32x4 a) { u32x2 w; w.x = cvt_pk_bf16(a[0], a[1]); w.y = cvt_pk_bf16(a[2], a[3]); return w; }
;     __device__ __forceinline__ void operator()(f32x4 (&acc)[2][2][4][2], const Unit& u, int wr, int wc, int fr, int fq) const {
;     ...
;         for (int n = 0; n < 2; ++n) {
;             const f32x4 g0 = tp[0 * 32 + n], g1 = tp[1 * 32 + n], g2 = tp[2 * 32 + n], gb = tp[3 * 32 + n], v0 = tp[4 * 32 + n], v1 = tp[5 * 32 + n], v2 = tp[6 * 32 + n], vb = tp[7 * 32 + n];
;             bf16_t* gp0 = G + (size_t)(u.pm * BM + wr * 64 + fr) * DFF + ch0 + 4 * n;
; #pragma unroll
;             for (int ai = 0; ai < 2; ++ai)
; #pragma unroll
;                 for (int m = 0; m < 4; ++m) {
;                     f32x4 gp4, gn4, vp4, vn4;
;                     const f32x4 gc4 = acc[ai][0][m][n], vc4 = acc[ai][1][m][n];
; #pragma unroll
;                     for (int j = 0; j < 4; ++j) {
;                         const float gpl = m > 0 ? acc[ai][0][m - 1][n][j] : 0.f, gnf = m < 3 ? acc[ai][0][m + 1][n][j] : 0.f;
;                         const float vpl = m > 0 ? acc[ai][1][m - 1][n][j] : 0.f, vnf = m < 3 ? acc[ai][1][m + 1][n][j] : 0.f;
;                         gp4[j] = dpp_prev(gpl, gc4[j]); gn4[j] = dpp_next(gnf, gc4[j]); vp4[j] = dpp_prev(vpl, vc4[j]); vn4[j] = dpp_next(vnf, vc4[j]);
;                     }
;                     const f32x4 gate = g0 * gp4 + g1 * gc4 + g2 * gn4 + gb;
;                     const f32x4 val = v0 * vp4 + v1 * vc4 + v2 * vn4 + vb;
;                     const f32x4 ea = gate * (-1.4426950408889634f);
;                     f32x4 den;
; #pragma unroll
;                     for (int j = 0; j < 4; ++j) den[j] = __builtin_amdgcn_exp2f(ea[j]);
;                     den = den + 1.0f;
; #pragma unroll
;                     for (int j = 0; j < 4; ++j) den[j] = __builtin_amdgcn_rcpf(den[j]);
;                     const f32x4 o = gate * den * val;
;                     const bool interior = !((m == 0 && fr == 0) || (m == 3 && fr == 15));
;                     if (interior) *(u32x2*)(gp0 + (size_t)(ai * HALF + m * 16) * DFF) = pack4(o);
.LBB0_1011:
	s_or_b64 exec, exec, s[70:71]
	v_mov_b32_e32 v153, v152
	v_mov_b32_e32 v16, v152
	v_mov_b32_e32 v17, v152
	v_pk_mul_f32 v[6:7], v[6:7], v[16:17]
	v_pk_mul_f32 v[4:5], v[4:5], v[152:153]
	v_pk_mul_f32 v[2:3], v[2:3], v[16:17]
	v_pk_mul_f32 v[0:1], v[0:1], v[152:153]
	v_mov_b32_dpp v16, v102 row_ror:1 row_mask:0xf bank_mask:0xf bound_ctrl:1
	v_mov_b32_dpp v17, v103 row_ror:1 row_mask:0xf bank_mask:0xf bound_ctrl:1
	v_mov_b32_dpp v56, v98 row_ror:1 row_mask:0xf bank_mask:0xf bound_ctrl:1
	v_mov_b32_dpp v16, v12 row_shr:1 row_mask:0xf bank_mask:0xf
	v_mov_b32_dpp v17, v13 row_shr:1 row_mask:0xf bank_mask:0xf
	v_mov_b32_dpp v57, v99 row_ror:1 row_mask:0xf bank_mask:0xf bound_ctrl:1
	v_mov_b32_dpp v18, v4 row_ror:15 row_mask:0xf bank_mask:0xf bound_ctrl:1
	v_mov_b32_dpp v19, v5 row_ror:15 row_mask:0xf bank_mask:0xf bound_ctrl:1
	v_mov_b32_dpp v56, v14 row_shr:1 row_mask:0xf bank_mask:0xf
	v_mov_b32_dpp v57, v15 row_shr:1 row_mask:0xf bank_mask:0xf
	v_pk_mul_f32 v[16:17], v[44:45], v[16:17]
	v_mov_b32_dpp v18, v12 row_shl:1 row_mask:0xf bank_mask:0xf
	v_mov_b32_dpp v19, v13 row_shl:1 row_mask:0xf bank_mask:0xf
	v_mov_b32_dpp v58, v6 row_ror:15 row_mask:0xf bank_mask:0xf bound_ctrl:1
	v_mov_b32_dpp v59, v7 row_ror:15 row_mask:0xf bank_mask:0xf bound_ctrl:1
	v_pk_mul_f32 v[56:57], v[46:47], v[56:57]
	v_pk_fma_f32 v[16:17], v[12:13], v[40:41], v[16:17]
	v_mov_b32_dpp v58, v14 row_shl:1 row_mask:0xf bank_mask:0xf
	v_mov_b32_dpp v59, v15 row_shl:1 row_mask:0xf bank_mask:0xf
	v_pk_fma_f32 v[56:57], v[14:15], v[42:43], v[56:57]
	v_pk_fma_f32 v[16:17], v[36:37], v[18:19], v[16:17]
	v_pk_fma_f32 v[18:19], v[38:39], v[58:59], v[56:57]
	v_pk_add_f32 v[16:17], v[32:33], v[16:17]
	v_pk_add_f32 v[18:19], v[34:35], v[18:19]
	v_mul_f32_e32 v56, 0xbfb8aa3b, v16
	v_mul_f32_e32 v57, 0xbfb8aa3b, v17
	v_exp_f32_e32 v56, v56
	v_mul_f32_e32 v58, 0xbfb8aa3b, v18
	v_mul_f32_e32 v59, 0xbfb8aa3b, v19
	v_exp_f32_e32 v57, v57
	v_exp_f32_e32 v58, v58
	v_exp_f32_e32 v59, v59
	v_mov_b32_dpp v20, v104 row_ror:1 row_mask:0xf bank_mask:0xf bound_ctrl:1
	v_mov_b32_dpp v21, v105 row_ror:1 row_mask:0xf bank_mask:0xf bound_ctrl:1
	v_pk_add_f32 v[56:57], v[56:57], 1.0 op_sel_hi:[1,0]
	v_mov_b32_dpp v20, v8 row_shr:1 row_mask:0xf bank_mask:0xf
	v_mov_b32_dpp v21, v9 row_shr:1 row_mask:0xf bank_mask:0xf
	v_mov_b32_dpp v60, v100 row_ror:1 row_mask:0xf bank_mask:0xf bound_ctrl:1
	v_mov_b32_dpp v61, v101 row_ror:1 row_mask:0xf bank_mask:0xf bound_ctrl:1
	v_pk_add_f32 v[58:59], v[58:59], 1.0 op_sel_hi:[1,0]
	v_rcp_f32_e32 v56, v56
	v_rcp_f32_e32 v57, v57
	v_mov_b32_dpp v22, v0 row_ror:15 row_mask:0xf bank_mask:0xf bound_ctrl:1
	v_mov_b32_dpp v23, v1 row_ror:15 row_mask:0xf bank_mask:0xf bound_ctrl:1
	v_mov_b32_dpp v60, v10 row_shr:1 row_mask:0xf bank_mask:0xf
	v_mov_b32_dpp v61, v11 row_shr:1 row_mask:0xf bank_mask:0xf
	v_rcp_f32_e32 v58, v58
	v_rcp_f32_e32 v59, v59
	v_pk_mul_f32 v[20:21], v[52:53], v[20:21]
	v_mov_b32_dpp v22, v8 row_shl:1 row_mask:0xf bank_mask:0xf
	v_mov_b32_dpp v23, v9 row_shl:1 row_mask:0xf bank_mask:0xf
	v_mov_b32_dpp v62, v2 row_ror:15 row_mask:0xf bank_mask:0xf bound_ctrl:1
	v_mov_b32_dpp v63, v3 row_ror:15 row_mask:0xf bank_mask:0xf bound_ctrl:1
	v_pk_mul_f32 v[60:61], v[54:55], v[60:61]
	v_pk_fma_f32 v[20:21], v[8:9], v[48:49], v[20:21]
	v_mov_b32_dpp v62, v10 row_shl:1 row_mask:0xf bank_mask:0xf
	v_mov_b32_dpp v63, v11 row_shl:1 row_mask:0xf bank_mask:0xf
	v_pk_fma_f32 v[60:61], v[10:11], v[50:51], v[60:61]
	v_pk_fma_f32 v[20:21], v[28:29], v[22:23], v[20:21]
	v_pk_fma_f32 v[60:61], v[30:31], v[62:63], v[60:61]
	v_pk_add_f32 v[20:21], v[24:25], v[20:21]
	v_pk_mul_f32 v[16:17], v[16:17], v[56:57]
	v_pk_add_f32 v[22:23], v[26:27], v[60:61]
	v_pk_mul_f32 v[18:19], v[18:19], v[58:59]
	v_pk_mul_f32 v[16:17], v[20:21], v[16:17]
	v_pk_mul_f32 v[18:19], v[22:23], v[18:19]
	v_cvt_pk_bf16_f32 v16, v16, v17
	s_nop 0
	v_cvt_pk_bf16_f32 v17, v18, v19
	v_mov_b32_e32 v232, v226
	v_mov_b32_e32 v233, v227
	v_mov_b32_e32 v234, v16
	v_mov_b32_e32 v235, v17
	global_store_dwordx4 v[164:165], v[232:235], off
	v_mov_b32_dpp v12, v12 row_ror:1 row_mask:0xf bank_mask:0xf bound_ctrl:1
	v_mov_b32_dpp v13, v13 row_ror:1 row_mask:0xf bank_mask:0xf bound_ctrl:1
	v_mov_b32_dpp v14, v14 row_ror:1 row_mask:0xf bank_mask:0xf bound_ctrl:1
	v_mov_b32_dpp v15, v15 row_ror:1 row_mask:0xf bank_mask:0xf bound_ctrl:1
	v_mov_b32_dpp v12, v4 row_shr:1 row_mask:0xf bank_mask:0xf
	v_mov_b32_dpp v13, v5 row_shr:1 row_mask:0xf bank_mask:0xf
	v_mov_b32_dpp v14, v6 row_shr:1 row_mask:0xf bank_mask:0xf
	v_mov_b32_dpp v15, v7 row_shr:1 row_mask:0xf bank_mask:0xf
	v_mov_b32_dpp v16, v90 row_ror:15 row_mask:0xf bank_mask:0xf bound_ctrl:1
	v_mov_b32_dpp v17, v91 row_ror:15 row_mask:0xf bank_mask:0xf bound_ctrl:1
	v_mov_b32_dpp v20, v88 row_ror:15 row_mask:0xf bank_mask:0xf bound_ctrl:1
	v_mov_b32_dpp v21, v89 row_ror:15 row_mask:0xf bank_mask:0xf bound_ctrl:1
	v_pk_mul_f32 v[12:13], v[44:45], v[12:13]
	v_pk_mul_f32 v[14:15], v[46:47], v[14:15]
	v_mov_b32_dpp v16, v4 row_shl:1 row_mask:0xf bank_mask:0xf
	v_mov_b32_dpp v17, v5 row_shl:1 row_mask:0xf bank_mask:0xf
	v_mov_b32_dpp v20, v6 row_shl:1 row_mask:0xf bank_mask:0xf
	v_mov_b32_dpp v21, v7 row_shl:1 row_mask:0xf bank_mask:0xf
	v_pk_fma_f32 v[14:15], v[6:7], v[42:43], v[14:15]
	v_pk_fma_f32 v[12:13], v[4:5], v[40:41], v[12:13]
	v_pk_fma_f32 v[14:15], v[38:39], v[20:21], v[14:15]
	v_pk_fma_f32 v[12:13], v[36:37], v[16:17], v[12:13]
	v_pk_add_f32 v[14:15], v[34:35], v[14:15]
	v_pk_add_f32 v[12:13], v[32:33], v[12:13]
	v_mul_f32_e32 v20, 0xbfb8aa3b, v14
	v_mul_f32_e32 v16, 0xbfb8aa3b, v12
	v_mul_f32_e32 v17, 0xbfb8aa3b, v13
; __device__ __forceinline__ u32x2 pack4(f32x4 a) { u32x2 w; w.x = cvt_pk_bf16(a[0], a[1]); w.y = cvt_pk_bf16(a[2], a[3]); return w; }
;     __device__ __forceinline__ void operator()(f32x4 (&acc)[2][2][4][2], const Unit& u, int wr, int wc, int fr, int fq) const {
;     ...
;         for (int n = 0; n < 2; ++n) {
;             const f32x4 g0 = tp[0 * 32 + n], g1 = tp[1 * 32 + n], g2 = tp[2 * 32 + n], gb = tp[3 * 32 + n], v0 = tp[4 * 32 + n], v1 = tp[5 * 32 + n], v2 = tp[6 * 32 + n], vb = tp[7 * 32 + n];
;             bf16_t* gp0 = G + (size_t)(u.pm * BM + wr * 64 + fr) * DFF + ch0 + 4 * n;
; #pragma unroll
;             for (int ai = 0; ai < 2; ++ai)
; #pragma unroll
;                 for (int m = 0; m < 4; ++m) {
;                     f32x4 gp4, gn4, vp4, vn4;
;                     const f32x4 gc4 = acc[ai][0][m][n], vc4 = acc[ai][1][m][n];
; #pragma unroll
;                     for (int j = 0; j < 4; ++j) {
;                         const float gpl = m > 0 ? acc[ai][0][m - 1][n][j] : 0.f, gnf = m < 3 ? acc[ai][0][m + 1][n][j] : 0.f;
;                         const float vpl = m > 0 ? acc[ai][1][m - 1][n][j] : 0.f, vnf = m < 3 ? acc[ai][1][m + 1][n][j] : 0.f;
;                         gp4[j] = dpp_prev(gpl, gc4[j]); gn4[j] = dpp_next(gnf, gc4[j]); vp4[j] = dpp_prev(vpl, vc4[j]); vn4[j] = dpp_next(vnf, vc4[j]);
;                     }
;                     const f32x4 gate = g0 * gp4 + g1 * gc4 + g2 * gn4 + gb;
;                     const f32x4 val = v0 * vp4 + v1 * vc4 + v2 * vn4 + vb;
;                     const f32x4 ea = gate * (-1.4426950408889634f);
;                     f32x4 den;
; #pragma unroll
;                     for (int j = 0; j < 4; ++j) den[j] = __builtin_amdgcn_exp2f(ea[j]);
;                     den = den + 1.0f;
; #pragma unroll
;                     for (int j = 0; j < 4; ++j) den[j] = __builtin_amdgcn_rcpf(den[j]);
;                     const f32x4 o = gate * den * val;
;                     const bool interior = !((m == 0 && fr == 0) || (m == 3 && fr == 15));
;                     if (interior) *(u32x2*)(gp0 + (size_t)(ai * HALF + m * 16) * DFF) = pack4(o);
;                     __builtin_amdgcn_sched_barrier(0);
;                 }
;             asm volatile("" ::: "memory");
;         }
	v_mul_f32_e32 v21, 0xbfb8aa3b, v15
	v_exp_f32_e32 v16, v16
	v_exp_f32_e32 v20, v20
	v_exp_f32_e32 v21, v21
	v_exp_f32_e32 v17, v17
	v_mov_b32_dpp v8, v8 row_ror:1 row_mask:0xf bank_mask:0xf bound_ctrl:1
	v_mov_b32_dpp v9, v9 row_ror:1 row_mask:0xf bank_mask:0xf bound_ctrl:1
	v_mov_b32_dpp v10, v10 row_ror:1 row_mask:0xf bank_mask:0xf bound_ctrl:1
	v_mov_b32_dpp v11, v11 row_ror:1 row_mask:0xf bank_mask:0xf bound_ctrl:1
	v_pk_add_f32 v[20:21], v[20:21], 1.0 op_sel_hi:[1,0]
	v_pk_add_f32 v[16:17], v[16:17], 1.0 op_sel_hi:[1,0]
	v_mov_b32_dpp v8, v0 row_shr:1 row_mask:0xf bank_mask:0xf
	v_mov_b32_dpp v9, v1 row_shr:1 row_mask:0xf bank_mask:0xf
	v_mov_b32_dpp v10, v2 row_shr:1 row_mask:0xf bank_mask:0xf
	v_mov_b32_dpp v11, v3 row_shr:1 row_mask:0xf bank_mask:0xf
	v_rcp_f32_e32 v16, v16
	v_rcp_f32_e32 v17, v17
	v_rcp_f32_e32 v20, v20
	v_rcp_f32_e32 v21, v21
	v_mov_b32_dpp v18, v94 row_ror:15 row_mask:0xf bank_mask:0xf bound_ctrl:1
	v_mov_b32_dpp v19, v95 row_ror:15 row_mask:0xf bank_mask:0xf bound_ctrl:1
	v_mov_b32_dpp v22, v92 row_ror:15 row_mask:0xf bank_mask:0xf bound_ctrl:1
	v_mov_b32_dpp v23, v93 row_ror:15 row_mask:0xf bank_mask:0xf bound_ctrl:1
	v_pk_mul_f32 v[10:11], v[54:55], v[10:11]
	v_pk_mul_f32 v[8:9], v[52:53], v[8:9]
	v_mov_b32_dpp v18, v0 row_shl:1 row_mask:0xf bank_mask:0xf
	v_mov_b32_dpp v19, v1 row_shl:1 row_mask:0xf bank_mask:0xf
	v_mov_b32_dpp v22, v2 row_shl:1 row_mask:0xf bank_mask:0xf
	v_mov_b32_dpp v23, v3 row_shl:1 row_mask:0xf bank_mask:0xf
	v_pk_fma_f32 v[8:9], v[0:1], v[48:49], v[8:9]
	v_pk_fma_f32 v[10:11], v[2:3], v[50:51], v[10:11]
	v_pk_fma_f32 v[8:9], v[28:29], v[18:19], v[8:9]
	v_pk_fma_f32 v[10:11], v[30:31], v[22:23], v[10:11]
	v_pk_add_f32 v[8:9], v[24:25], v[8:9]
	v_pk_add_f32 v[10:11], v[26:27], v[10:11]
	v_pk_mul_f32 v[12:13], v[12:13], v[16:17]
	v_pk_mul_f32 v[14:15], v[14:15], v[20:21]
	v_pk_mul_f32 v[8:9], v[8:9], v[12:13]
	v_pk_mul_f32 v[10:11], v[10:11], v[14:15]
	v_cvt_pk_bf16_f32 v8, v8, v9
	s_nop 0
	v_cvt_pk_bf16_f32 v9, v10, v11
	v_mov_b32_e32 v232, v228
	v_mov_b32_e32 v233, v229
	v_mov_b32_e32 v234, v8
	v_mov_b32_e32 v235, v9
	global_store_dwordx4 v[166:167], v[232:235], off
	s_nop 0
	v_mov_b32_dpp v9, v141 row_ror:15 row_mask:0xf bank_mask:0xf bound_ctrl:1
	v_mov_b32_dpp v10, v4 row_ror:1 row_mask:0xf bank_mask:0xf bound_ctrl:1
	v_mov_b32_e32 v4, v9
	v_mov_b32_dpp v14, v0 row_ror:1 row_mask:0xf bank_mask:0xf bound_ctrl:1
	v_mov_b32_e32 v0, v9
	v_mov_b32_dpp v11, v5 row_ror:1 row_mask:0xf bank_mask:0xf bound_ctrl:1
	v_mov_b32_e32 v5, v9
	v_mov_b32_dpp v15, v1 row_ror:1 row_mask:0xf bank_mask:0xf bound_ctrl:1
	v_mov_b32_e32 v1, v9
	v_mov_b32_dpp v12, v6 row_ror:1 row_mask:0xf bank_mask:0xf bound_ctrl:1
	v_mov_b32_e32 v6, v9
	v_mov_b32_dpp v2, v2 row_ror:1 row_mask:0xf bank_mask:0xf bound_ctrl:1
	v_mov_b32_e32 v8, v9
	v_mov_b32_dpp v13, v7 row_ror:1 row_mask:0xf bank_mask:0xf bound_ctrl:1
	v_mov_b32_e32 v7, v9
	v_mov_b32_dpp v3, v3 row_ror:1 row_mask:0xf bank_mask:0xf bound_ctrl:1
	v_mov_b32_dpp v10, v90 row_shr:1 row_mask:0xf bank_mask:0xf
	v_mov_b32_dpp v4, v90 row_shl:1 row_mask:0xf bank_mask:0xf
	v_mov_b32_dpp v14, v94 row_shr:1 row_mask:0xf bank_mask:0xf
	v_mov_b32_dpp v0, v94 row_shl:1 row_mask:0xf bank_mask:0xf
	v_mov_b32_dpp v11, v91 row_shr:1 row_mask:0xf bank_mask:0xf
	v_mov_b32_dpp v5, v91 row_shl:1 row_mask:0xf bank_mask:0xf
	v_mov_b32_dpp v15, v95 row_shr:1 row_mask:0xf bank_mask:0xf
	v_mov_b32_dpp v1, v95 row_shl:1 row_mask:0xf bank_mask:0xf
	v_mov_b32_dpp v12, v88 row_shr:1 row_mask:0xf bank_mask:0xf
	v_mov_b32_dpp v6, v88 row_shl:1 row_mask:0xf bank_mask:0xf
	v_mov_b32_dpp v2, v92 row_shr:1 row_mask:0xf bank_mask:0xf
	v_mov_b32_dpp v8, v92 row_shl:1 row_mask:0xf bank_mask:0xf
	v_mov_b32_dpp v13, v89 row_shr:1 row_mask:0xf bank_mask:0xf
	v_mov_b32_dpp v7, v89 row_shl:1 row_mask:0xf bank_mask:0xf
	v_mov_b32_dpp v3, v93 row_shr:1 row_mask:0xf bank_mask:0xf
	v_mov_b32_dpp v9, v93 row_shl:1 row_mask:0xf bank_mask:0xf
	s_and_saveexec_b64 s[70:71], s[8:9]
	s_cbranch_execz .LBB0_1013
	v_pk_mul_f32 v[12:13], v[46:47], v[12:13]
	v_pk_mul_f32 v[10:11], v[44:45], v[10:11]
	v_pk_fma_f32 v[12:13], v[88:89], v[42:43], v[12:13]
	v_pk_fma_f32 v[10:11], v[90:91], v[40:41], v[10:11]
	v_pk_fma_f32 v[6:7], v[38:39], v[6:7], v[12:13]
	v_pk_fma_f32 v[4:5], v[36:37], v[4:5], v[10:11]
	v_pk_add_f32 v[6:7], v[34:35], v[6:7]
	v_pk_add_f32 v[4:5], v[32:33], v[4:5]
	v_mul_f32_e32 v12, 0xbfb8aa3b, v6
	v_mul_f32_e32 v10, 0xbfb8aa3b, v4
	v_mul_f32_e32 v11, 0xbfb8aa3b, v5
	v_mul_f32_e32 v13, 0xbfb8aa3b, v7
	v_exp_f32_e32 v10, v10
	v_exp_f32_e32 v12, v12
	v_exp_f32_e32 v13, v13
	v_exp_f32_e32 v11, v11
	v_pk_mul_f32 v[2:3], v[54:55], v[2:3]
	v_pk_mul_f32 v[14:15], v[52:53], v[14:15]
	v_pk_fma_f32 v[2:3], v[92:93], v[50:51], v[2:3]
	v_pk_add_f32 v[10:11], v[10:11], 1.0 op_sel_hi:[1,0]
	v_pk_fma_f32 v[2:3], v[30:31], v[8:9], v[2:3]
	v_pk_add_f32 v[8:9], v[12:13], 1.0 op_sel_hi:[1,0]
	v_rcp_f32_e32 v10, v10
	v_rcp_f32_e32 v11, v11
	v_rcp_f32_e32 v8, v8
	v_rcp_f32_e32 v9, v9
	v_pk_fma_f32 v[14:15], v[94:95], v[48:49], v[14:15]
	v_pk_add_f32 v[2:3], v[26:27], v[2:3]
	v_pk_fma_f32 v[0:1], v[28:29], v[0:1], v[14:15]
	v_pk_mul_f32 v[4:5], v[4:5], v[10:11]
	v_pk_add_f32 v[0:1], v[24:25], v[0:1]
	v_pk_mul_f32 v[6:7], v[6:7], v[8:9]
	v_pk_mul_f32 v[0:1], v[0:1], v[4:5]
	v_pk_mul_f32 v[2:3], v[2:3], v[6:7]
	v_cvt_pk_bf16_f32 v0, v0, v1
	s_nop 0
	v_cvt_pk_bf16_f32 v1, v2, v3
	v_add_co_u32_e32 v2, vcc, 0x1e4000, v96
	s_nop 1
	v_addc_co_u32_e32 v3, vcc, 0, v97, vcc
	v_mov_b32_e32 v232, v230
	v_mov_b32_e32 v233, v231
	v_mov_b32_e32 v234, v0
	v_mov_b32_e32 v235, v1
	global_store_dwordx4 v[2:3], v[232:235], off
